# adaLN GEMV column slabs assigned in XCD-major workgroup order (the two workgroups sharing each 128-B line of a w_mod row share an L2); accumulator clears between GEMM tiles paired into v_mov_b64; on t
# speedup vs baseline: 1.0123x; 1.0075x over previous
; #define LAS __attribute__((address_space(3)))
; __device__ __forceinline__ float fast_sigmoid(float x) { return __builtin_amdgcn_rcpf(1.0f + __builtin_amdgcn_exp2f(-1.4426950408889634f * x)); }
; __global__ void __launch_bounds__(NTHREADS) fwd_megakernel(Args a) {
;     ...
;         LAS float* sil = (LAS float*)ldsl;
;         LAS float* red = (LAS float*)(ldsl + 12288);
;         for (int idx = tid; idx < 3072; idx += NTHREADS) { const int v = idx >> 10, k = idx & 1023; const float cv = (v < 2) ? a.c[v * DM + k] : a.c_ctx[k]; sil[idx] = cv * fast_sigmoid(cv); }
;         __syncthreads();
;         const bool act = lane < 36; const int j = bx * 36 + (act ? lane : 0), kb = wave * 128;
;         float s0 = 0.f, s1 = 0.f, s2 = 0.f;
;         if (act) {
; #pragma unroll 8
;         for (int kk = 0; kk < 128; ++kk) { const float w = __builtin_nontemporal_load(a.w_mod + (size_t)(kb + kk) * NMOD + j); s0 += sil[kb + kk] * w; s1 += sil[1024 + kb + kk] * w; s2 += sil[2048 + kb + kk] * w; }
;         }
.LBB0_7:
	s_load_dwordx16 s[68:83], s[0:1], 0x40
	s_load_dwordx16 s[52:67], s[0:1], 0x80
	v_mov_b32_e32 v3, 0
	v_lshlrev_b32_e32 v2, 2, v160
	s_waitcnt lgkmcnt(0)
	v_lshl_add_u64 v[4:5], s[38:39], 0, v[2:3]
	v_lshl_add_u64 v[8:9], s[42:43], 0, v[2:3]
	s_mov_b64 s[4:5], 0x1000
	v_lshl_add_u64 v[6:7], v[4:5], 0, s[4:5]
	v_add_u32_e32 v1, 0, v2
	global_load_dword v10, v[4:5], off
	global_load_dword v11, v[4:5], off offset:2048
	global_load_dword v12, v[6:7], off
	global_load_dword v13, v[6:7], off offset:2048
	global_load_dword v14, v[8:9], off
	global_load_dword v15, v[8:9], off offset:2048
	s_waitcnt vmcnt(5)
	v_mul_f32_e32 v16, 0xbfb8aa3b, v10
	v_exp_f32_e32 v16, v16
	s_nop 0
	v_add_f32_e32 v16, 1.0, v16
	v_rcp_f32_e32 v16, v16
	s_nop 0
	v_mul_f32_e32 v10, v10, v16
	ds_write_b32 v1, v10
	s_waitcnt vmcnt(4)
	v_mul_f32_e32 v16, 0xbfb8aa3b, v11
	v_exp_f32_e32 v16, v16
	s_nop 0
	v_add_f32_e32 v16, 1.0, v16
	v_rcp_f32_e32 v16, v16
	s_nop 0
	v_mul_f32_e32 v11, v11, v16
	ds_write_b32 v1, v11 offset:2048
	s_waitcnt vmcnt(3)
	v_mul_f32_e32 v16, 0xbfb8aa3b, v12
	v_exp_f32_e32 v16, v16
	s_nop 0
	v_add_f32_e32 v16, 1.0, v16
	v_rcp_f32_e32 v16, v16
	s_nop 0
	v_mul_f32_e32 v12, v12, v16
	ds_write_b32 v1, v12 offset:4096
	s_waitcnt vmcnt(2)
	v_mul_f32_e32 v16, 0xbfb8aa3b, v13
	v_exp_f32_e32 v16, v16
	s_nop 0
	v_add_f32_e32 v16, 1.0, v16
	v_rcp_f32_e32 v16, v16
	s_nop 0
	v_mul_f32_e32 v13, v13, v16
	ds_write_b32 v1, v13 offset:6144
	s_waitcnt vmcnt(1)
	v_mul_f32_e32 v16, 0xbfb8aa3b, v14
	v_exp_f32_e32 v16, v16
	s_nop 0
	v_add_f32_e32 v16, 1.0, v16
	v_rcp_f32_e32 v16, v16
	s_nop 0
	v_mul_f32_e32 v14, v14, v16
	ds_write_b32 v1, v14 offset:8192
	s_waitcnt vmcnt(0)
	v_mul_f32_e32 v16, 0xbfb8aa3b, v15
	v_exp_f32_e32 v16, v16
	s_nop 0
	v_add_f32_e32 v16, 1.0, v16
	v_rcp_f32_e32 v16, v16
	s_nop 0
	v_mul_f32_e32 v15, v15, v16
	ds_write_b32 v1, v15 offset:10240
	v_and_b32_e32 v161, 63, v160
	v_cmp_gt_u32_e32 vcc, 36, v161
	v_mov_b32_e32 v5, 0
	s_lshr_b32 s21, s16, 6
	v_cndmask_b32_e32 v2, 0, v161, vcc
	s_and_b32 s98, s20, 7
	s_lshl_b32 s98, s98, 5
	s_lshr_b32 s99, s20, 3
	s_add_i32 s98, s98, s99
	v_mad_u64_u32 v[2:3], s[0:1], s98, 36, v[2:3]
	v_ashrrev_i32_e32 v3, 31, v2
	v_mov_b32_e32 v4, v5
	v_mov_b32_e32 v1, v5
	s_waitcnt lgkmcnt(0)
	s_barrier
	s_and_saveexec_b64 s[4:5], vcc
	s_cbranch_execz .LBB0_12
	s_lshl_b32 s1, s21, 9
	s_lshl_b32 s0, s21, 7
	s_add_i32 s3, s1, 0
	s_mul_i32 s1, s21, 0x480000
	s_mul_hi_u32 s6, s0, 0x9000
	s_add_u32 s0, s44, s1
	s_addc_u32 s1, s45, s6
	v_lshlrev_b32_e32 v6, 2, v2
	v_mov_b32_e32 v1, 0
	v_mov_b32_e32 v4, 0
	v_mov_b32_e32 v5, 0
	global_load_dword v32, v6, s[0:1] nt
	s_add_u32 s0, s0, 0x9000
	s_addc_u32 s1, s1, 0
	global_load_dword v33, v6, s[0:1] nt
	s_add_u32 s0, s0, 0x9000
	s_addc_u32 s1, s1, 0
	global_load_dword v34, v6, s[0:1] nt
	s_add_u32 s0, s0, 0x9000
	s_addc_u32 s1, s1, 0
	global_load_dword v35, v6, s[0:1] nt
	s_add_u32 s0, s0, 0x9000
	s_addc_u32 s1, s1, 0
	global_load_dword v36, v6, s[0:1] nt
	s_add_u32 s0, s0, 0x9000
	s_addc_u32 s1, s1, 0
	global_load_dword v37, v6, s[0:1] nt
	s_add_u32 s0, s0, 0x9000
	s_addc_u32 s1, s1, 0
	global_load_dword v38, v6, s[0:1] nt
	s_add_u32 s0, s0, 0x9000
	s_addc_u32 s1, s1, 0
	global_load_dword v39, v6, s[0:1] nt
	s_add_u32 s0, s0, 0x9000
	s_addc_u32 s1, s1, 0
	global_load_dword v40, v6, s[0:1] nt
	s_add_u32 s0, s0, 0x9000
	s_addc_u32 s1, s1, 0
	global_load_dword v41, v6, s[0:1] nt
	s_add_u32 s0, s0, 0x9000
	s_addc_u32 s1, s1, 0
	global_load_dword v42, v6, s[0:1] nt
	s_add_u32 s0, s0, 0x9000
	s_addc_u32 s1, s1, 0
	global_load_dword v43, v6, s[0:1] nt
	s_add_u32 s0, s0, 0x9000
	s_addc_u32 s1, s1, 0
	global_load_dword v44, v6, s[0:1] nt
	s_add_u32 s0, s0, 0x9000
	s_addc_u32 s1, s1, 0
	global_load_dword v45, v6, s[0:1] nt
	s_add_u32 s0, s0, 0x9000
	s_addc_u32 s1, s1, 0
	global_load_dword v46, v6, s[0:1] nt
	s_add_u32 s0, s0, 0x9000
	s_addc_u32 s1, s1, 0
	global_load_dword v47, v6, s[0:1] nt
	s_add_u32 s0, s0, 0x9000
	s_addc_u32 s1, s1, 0
	global_load_dword v48, v6, s[0:1] nt
	s_add_u32 s0, s0, 0x9000
	s_addc_u32 s1, s1, 0
	global_load_dword v49, v6, s[0:1] nt
	s_add_u32 s0, s0, 0x9000
	s_addc_u32 s1, s1, 0
	global_load_dword v50, v6, s[0:1] nt
	s_add_u32 s0, s0, 0x9000
	s_addc_u32 s1, s1, 0
	global_load_dword v51, v6, s[0:1] nt
	s_add_u32 s0, s0, 0x9000
	s_addc_u32 s1, s1, 0
	global_load_dword v52, v6, s[0:1] nt
	s_add_u32 s0, s0, 0x9000
	s_addc_u32 s1, s1, 0
	global_load_dword v53, v6, s[0:1] nt
	s_add_u32 s0, s0, 0x9000
	s_addc_u32 s1, s1, 0
	global_load_dword v54, v6, s[0:1] nt
	s_add_u32 s0, s0, 0x9000
	s_addc_u32 s1, s1, 0
	global_load_dword v55, v6, s[0:1] nt
	s_add_u32 s0, s0, 0x9000
	s_addc_u32 s1, s1, 0
	global_load_dword v56, v6, s[0:1] nt
	s_add_u32 s0, s0, 0x9000
	s_addc_u32 s1, s1, 0
	global_load_dword v57, v6, s[0:1] nt
	s_add_u32 s0, s0, 0x9000
	s_addc_u32 s1, s1, 0
	global_load_dword v58, v6, s[0:1] nt
	s_add_u32 s0, s0, 0x9000
	s_addc_u32 s1, s1, 0
	global_load_dword v59, v6, s[0:1] nt
	s_add_u32 s0, s0, 0x9000
	s_addc_u32 s1, s1, 0
	global_load_dword v60, v6, s[0:1] nt
	s_add_u32 s0, s0, 0x9000
	s_addc_u32 s1, s1, 0
	global_load_dword v61, v6, s[0:1] nt
	s_add_u32 s0, s0, 0x9000
	s_addc_u32 s1, s1, 0
	global_load_dword v62, v6, s[0:1] nt
	s_add_u32 s0, s0, 0x9000
	s_addc_u32 s1, s1, 0
	global_load_dword v63, v6, s[0:1] nt
	s_add_u32 s0, s0, 0x9000
	s_addc_u32 s1, s1, 0
	global_load_dword v64, v6, s[0:1] nt
	s_add_u32 s0, s0, 0x9000
	s_addc_u32 s1, s1, 0
	global_load_dword v65, v6, s[0:1] nt
	s_add_u32 s0, s0, 0x9000
	s_addc_u32 s1, s1, 0
	global_load_dword v66, v6, s[0:1] nt
	s_add_u32 s0, s0, 0x9000
	s_addc_u32 s1, s1, 0
	global_load_dword v67, v6, s[0:1] nt
; __global__ void __launch_bounds__(NTHREADS) fwd_megakernel(Args a) {
;     ...
;         if (act) {
; #pragma unroll 8
;         for (int kk = 0; kk < 128; ++kk) { const float w = __builtin_nontemporal_load(a.w_mod + (size_t)(kb + kk) * NMOD + j); s0 += sil[kb + kk] * w; s1 += sil[1024 + kb + kk] * w; s2 += sil[2048 + kb + kk] * w; }
;         }
	s_add_u32 s0, s0, 0x9000
	s_addc_u32 s1, s1, 0
	global_load_dword v68, v6, s[0:1] nt
	s_add_u32 s0, s0, 0x9000
	s_addc_u32 s1, s1, 0
	global_load_dword v69, v6, s[0:1] nt
	s_add_u32 s0, s0, 0x9000
	s_addc_u32 s1, s1, 0
	global_load_dword v70, v6, s[0:1] nt
	s_add_u32 s0, s0, 0x9000
	s_addc_u32 s1, s1, 0
	global_load_dword v71, v6, s[0:1] nt
	s_add_u32 s0, s0, 0x9000
	s_addc_u32 s1, s1, 0
	global_load_dword v72, v6, s[0:1] nt
	s_add_u32 s0, s0, 0x9000
	s_addc_u32 s1, s1, 0
	global_load_dword v73, v6, s[0:1] nt
	s_add_u32 s0, s0, 0x9000
	s_addc_u32 s1, s1, 0
	global_load_dword v74, v6, s[0:1] nt
	s_add_u32 s0, s0, 0x9000
	s_addc_u32 s1, s1, 0
	global_load_dword v75, v6, s[0:1] nt
	s_add_u32 s0, s0, 0x9000
	s_addc_u32 s1, s1, 0
	global_load_dword v76, v6, s[0:1] nt
	s_add_u32 s0, s0, 0x9000
	s_addc_u32 s1, s1, 0
	global_load_dword v77, v6, s[0:1] nt
	s_add_u32 s0, s0, 0x9000
	s_addc_u32 s1, s1, 0
	global_load_dword v78, v6, s[0:1] nt
	s_add_u32 s0, s0, 0x9000
	s_addc_u32 s1, s1, 0
	global_load_dword v79, v6, s[0:1] nt
	s_add_u32 s0, s0, 0x9000
	s_addc_u32 s1, s1, 0
	global_load_dword v80, v6, s[0:1] nt
	s_add_u32 s0, s0, 0x9000
	s_addc_u32 s1, s1, 0
	global_load_dword v81, v6, s[0:1] nt
	s_add_u32 s0, s0, 0x9000
	s_addc_u32 s1, s1, 0
	global_load_dword v82, v6, s[0:1] nt
	s_add_u32 s0, s0, 0x9000
	s_addc_u32 s1, s1, 0
	global_load_dword v83, v6, s[0:1] nt
	s_add_u32 s0, s0, 0x9000
	s_addc_u32 s1, s1, 0
	global_load_dword v84, v6, s[0:1] nt
	s_add_u32 s0, s0, 0x9000
	s_addc_u32 s1, s1, 0
	global_load_dword v85, v6, s[0:1] nt
	s_add_u32 s0, s0, 0x9000
	s_addc_u32 s1, s1, 0
	global_load_dword v86, v6, s[0:1] nt
	s_add_u32 s0, s0, 0x9000
	s_addc_u32 s1, s1, 0
	global_load_dword v87, v6, s[0:1] nt
	s_add_u32 s0, s0, 0x9000
	s_addc_u32 s1, s1, 0
	v_mov_b32_e32 v28, s3
	ds_read_b128 v[8:11], v28
	ds_read_b128 v[12:15], v28 offset:16
	ds_read_b128 v[16:19], v28 offset:4096
	ds_read_b128 v[20:23], v28 offset:4112
	ds_read_b128 v[24:27], v28 offset:8192
	ds_read_b128 v[28:31], v28 offset:8208
	s_add_i32 s3, s3, 32
	s_waitcnt lgkmcnt(0)
	s_waitcnt vmcnt(55)
	v_fmac_f32_e32 v1, v32, v8
	v_fmac_f32_e32 v5, v32, v16
	v_fmac_f32_e32 v4, v32, v24
	global_load_dword v88, v6, s[0:1] nt
	s_add_u32 s0, s0, 0x9000
	s_addc_u32 s1, s1, 0
	s_waitcnt vmcnt(55)
	v_fmac_f32_e32 v1, v33, v9
	v_fmac_f32_e32 v5, v33, v17
	v_fmac_f32_e32 v4, v33, v25
	global_load_dword v89, v6, s[0:1] nt
	s_add_u32 s0, s0, 0x9000
	s_addc_u32 s1, s1, 0
	s_waitcnt vmcnt(55)
	v_fmac_f32_e32 v1, v34, v10
	v_fmac_f32_e32 v5, v34, v18
	v_fmac_f32_e32 v4, v34, v26
	global_load_dword v90, v6, s[0:1] nt
	s_add_u32 s0, s0, 0x9000
	s_addc_u32 s1, s1, 0
	s_waitcnt vmcnt(55)
	v_fmac_f32_e32 v1, v35, v11
	v_fmac_f32_e32 v5, v35, v19
	v_fmac_f32_e32 v4, v35, v27
	global_load_dword v91, v6, s[0:1] nt
	s_add_u32 s0, s0, 0x9000
	s_addc_u32 s1, s1, 0
	s_waitcnt vmcnt(55)
	v_fmac_f32_e32 v1, v36, v12
	v_fmac_f32_e32 v5, v36, v20
	v_fmac_f32_e32 v4, v36, v28
	global_load_dword v92, v6, s[0:1] nt
	s_add_u32 s0, s0, 0x9000
	s_addc_u32 s1, s1, 0
	s_waitcnt vmcnt(55)
	v_fmac_f32_e32 v1, v37, v13
	v_fmac_f32_e32 v5, v37, v21
	v_fmac_f32_e32 v4, v37, v29
	global_load_dword v93, v6, s[0:1] nt
	s_add_u32 s0, s0, 0x9000
	s_addc_u32 s1, s1, 0
	s_waitcnt vmcnt(55)
	v_fmac_f32_e32 v1, v38, v14
	v_fmac_f32_e32 v5, v38, v22
	v_fmac_f32_e32 v4, v38, v30
	global_load_dword v94, v6, s[0:1] nt
	s_add_u32 s0, s0, 0x9000
	s_addc_u32 s1, s1, 0
	s_waitcnt vmcnt(55)
	v_fmac_f32_e32 v1, v39, v15
	v_fmac_f32_e32 v5, v39, v23
	v_fmac_f32_e32 v4, v39, v31
	global_load_dword v95, v6, s[0:1] nt
	s_add_u32 s0, s0, 0x9000
	s_addc_u32 s1, s1, 0
	v_mov_b32_e32 v28, s3
	ds_read_b128 v[8:11], v28
	ds_read_b128 v[12:15], v28 offset:16
	ds_read_b128 v[16:19], v28 offset:4096
	ds_read_b128 v[20:23], v28 offset:4112
	ds_read_b128 v[24:27], v28 offset:8192
	ds_read_b128 v[28:31], v28 offset:8208
	s_add_i32 s3, s3, 32
	s_waitcnt lgkmcnt(0)
	s_waitcnt vmcnt(55)
	v_fmac_f32_e32 v1, v40, v8
	v_fmac_f32_e32 v5, v40, v16
	v_fmac_f32_e32 v4, v40, v24
	global_load_dword v96, v6, s[0:1] nt
	s_add_u32 s0, s0, 0x9000
	s_addc_u32 s1, s1, 0
	s_waitcnt vmcnt(55)
	v_fmac_f32_e32 v1, v41, v9
	v_fmac_f32_e32 v5, v41, v17
	v_fmac_f32_e32 v4, v41, v25
	global_load_dword v97, v6, s[0:1] nt
	s_add_u32 s0, s0, 0x9000
	s_addc_u32 s1, s1, 0
	s_waitcnt vmcnt(55)
	v_fmac_f32_e32 v1, v42, v10
	v_fmac_f32_e32 v5, v42, v18
	v_fmac_f32_e32 v4, v42, v26
	global_load_dword v98, v6, s[0:1] nt
	s_add_u32 s0, s0, 0x9000
	s_addc_u32 s1, s1, 0
	s_waitcnt vmcnt(55)
	v_fmac_f32_e32 v1, v43, v11
	v_fmac_f32_e32 v5, v43, v19
	v_fmac_f32_e32 v4, v43, v27
	global_load_dword v99, v6, s[0:1] nt
	s_add_u32 s0, s0, 0x9000
	s_addc_u32 s1, s1, 0
	s_waitcnt vmcnt(55)
	v_fmac_f32_e32 v1, v44, v12
	v_fmac_f32_e32 v5, v44, v20
	v_fmac_f32_e32 v4, v44, v28
	global_load_dword v100, v6, s[0:1] nt
	s_add_u32 s0, s0, 0x9000
	s_addc_u32 s1, s1, 0
	s_waitcnt vmcnt(55)
	v_fmac_f32_e32 v1, v45, v13
	v_fmac_f32_e32 v5, v45, v21
	v_fmac_f32_e32 v4, v45, v29
	global_load_dword v101, v6, s[0:1] nt
	s_add_u32 s0, s0, 0x9000
	s_addc_u32 s1, s1, 0
	s_waitcnt vmcnt(55)
	v_fmac_f32_e32 v1, v46, v14
	v_fmac_f32_e32 v5, v46, v22
	v_fmac_f32_e32 v4, v46, v30
	global_load_dword v102, v6, s[0:1] nt
	s_add_u32 s0, s0, 0x9000
	s_addc_u32 s1, s1, 0
	s_waitcnt vmcnt(55)
	v_fmac_f32_e32 v1, v47, v15
	v_fmac_f32_e32 v5, v47, v23
	v_fmac_f32_e32 v4, v47, v31
	global_load_dword v103, v6, s[0:1] nt
	s_add_u32 s0, s0, 0x9000
	s_addc_u32 s1, s1, 0
	v_mov_b32_e32 v28, s3
	ds_read_b128 v[8:11], v28
	ds_read_b128 v[12:15], v28 offset:16
	ds_read_b128 v[16:19], v28 offset:4096
	ds_read_b128 v[20:23], v28 offset:4112
	ds_read_b128 v[24:27], v28 offset:8192
	ds_read_b128 v[28:31], v28 offset:8208
	s_add_i32 s3, s3, 32
	s_waitcnt lgkmcnt(0)
; __global__ void __launch_bounds__(NTHREADS) fwd_megakernel(Args a) {
;     ...
;         if (act) {
; #pragma unroll 8
;         for (int kk = 0; kk < 128; ++kk) { const float w = __builtin_nontemporal_load(a.w_mod + (size_t)(kb + kk) * NMOD + j); s0 += sil[kb + kk] * w; s1 += sil[1024 + kb + kk] * w; s2 += sil[2048 + kb + kk] * w; }
;         }
	s_waitcnt vmcnt(55)
	v_fmac_f32_e32 v1, v48, v8
	v_fmac_f32_e32 v5, v48, v16
	v_fmac_f32_e32 v4, v48, v24
	global_load_dword v104, v6, s[0:1] nt
	s_add_u32 s0, s0, 0x9000
	s_addc_u32 s1, s1, 0
	s_waitcnt vmcnt(55)
	v_fmac_f32_e32 v1, v49, v9
	v_fmac_f32_e32 v5, v49, v17
	v_fmac_f32_e32 v4, v49, v25
	global_load_dword v105, v6, s[0:1] nt
	s_add_u32 s0, s0, 0x9000
	s_addc_u32 s1, s1, 0
	s_waitcnt vmcnt(55)
	v_fmac_f32_e32 v1, v50, v10
	v_fmac_f32_e32 v5, v50, v18
	v_fmac_f32_e32 v4, v50, v26
	global_load_dword v106, v6, s[0:1] nt
	s_add_u32 s0, s0, 0x9000
	s_addc_u32 s1, s1, 0
	s_waitcnt vmcnt(55)
	v_fmac_f32_e32 v1, v51, v11
	v_fmac_f32_e32 v5, v51, v19
	v_fmac_f32_e32 v4, v51, v27
	global_load_dword v107, v6, s[0:1] nt
	s_add_u32 s0, s0, 0x9000
	s_addc_u32 s1, s1, 0
	s_waitcnt vmcnt(55)
	v_fmac_f32_e32 v1, v52, v12
	v_fmac_f32_e32 v5, v52, v20
	v_fmac_f32_e32 v4, v52, v28
	global_load_dword v108, v6, s[0:1] nt
	s_add_u32 s0, s0, 0x9000
	s_addc_u32 s1, s1, 0
	s_waitcnt vmcnt(55)
	v_fmac_f32_e32 v1, v53, v13
	v_fmac_f32_e32 v5, v53, v21
	v_fmac_f32_e32 v4, v53, v29
	global_load_dword v109, v6, s[0:1] nt
	s_add_u32 s0, s0, 0x9000
	s_addc_u32 s1, s1, 0
	s_waitcnt vmcnt(55)
	v_fmac_f32_e32 v1, v54, v14
	v_fmac_f32_e32 v5, v54, v22
	v_fmac_f32_e32 v4, v54, v30
	global_load_dword v110, v6, s[0:1] nt
	s_add_u32 s0, s0, 0x9000
	s_addc_u32 s1, s1, 0
	s_waitcnt vmcnt(55)
	v_fmac_f32_e32 v1, v55, v15
	v_fmac_f32_e32 v5, v55, v23
	v_fmac_f32_e32 v4, v55, v31
	global_load_dword v111, v6, s[0:1] nt
	s_add_u32 s0, s0, 0x9000
	s_addc_u32 s1, s1, 0
	v_mov_b32_e32 v28, s3
	ds_read_b128 v[8:11], v28
	ds_read_b128 v[12:15], v28 offset:16
	ds_read_b128 v[16:19], v28 offset:4096
	ds_read_b128 v[20:23], v28 offset:4112
	ds_read_b128 v[24:27], v28 offset:8192
	ds_read_b128 v[28:31], v28 offset:8208
	s_add_i32 s3, s3, 32
	s_waitcnt lgkmcnt(0)
	s_waitcnt vmcnt(55)
	v_fmac_f32_e32 v1, v56, v8
	v_fmac_f32_e32 v5, v56, v16
	v_fmac_f32_e32 v4, v56, v24
	global_load_dword v112, v6, s[0:1] nt
	s_add_u32 s0, s0, 0x9000
	s_addc_u32 s1, s1, 0
	s_waitcnt vmcnt(55)
	v_fmac_f32_e32 v1, v57, v9
	v_fmac_f32_e32 v5, v57, v17
	v_fmac_f32_e32 v4, v57, v25
	global_load_dword v113, v6, s[0:1] nt
	s_add_u32 s0, s0, 0x9000
	s_addc_u32 s1, s1, 0
	s_waitcnt vmcnt(55)
	v_fmac_f32_e32 v1, v58, v10
	v_fmac_f32_e32 v5, v58, v18
	v_fmac_f32_e32 v4, v58, v26
	global_load_dword v114, v6, s[0:1] nt
	s_add_u32 s0, s0, 0x9000
	s_addc_u32 s1, s1, 0
	s_waitcnt vmcnt(55)
	v_fmac_f32_e32 v1, v59, v11
	v_fmac_f32_e32 v5, v59, v19
	v_fmac_f32_e32 v4, v59, v27
	global_load_dword v115, v6, s[0:1] nt
	s_add_u32 s0, s0, 0x9000
	s_addc_u32 s1, s1, 0
	s_waitcnt vmcnt(55)
	v_fmac_f32_e32 v1, v60, v12
	v_fmac_f32_e32 v5, v60, v20
	v_fmac_f32_e32 v4, v60, v28
	global_load_dword v116, v6, s[0:1] nt
	s_add_u32 s0, s0, 0x9000
	s_addc_u32 s1, s1, 0
	s_waitcnt vmcnt(55)
	v_fmac_f32_e32 v1, v61, v13
	v_fmac_f32_e32 v5, v61, v21
	v_fmac_f32_e32 v4, v61, v29
	global_load_dword v117, v6, s[0:1] nt
	s_add_u32 s0, s0, 0x9000
	s_addc_u32 s1, s1, 0
	s_waitcnt vmcnt(55)
	v_fmac_f32_e32 v1, v62, v14
	v_fmac_f32_e32 v5, v62, v22
	v_fmac_f32_e32 v4, v62, v30
	global_load_dword v118, v6, s[0:1] nt
	s_add_u32 s0, s0, 0x9000
	s_addc_u32 s1, s1, 0
	s_waitcnt vmcnt(55)
	v_fmac_f32_e32 v1, v63, v15
	v_fmac_f32_e32 v5, v63, v23
	v_fmac_f32_e32 v4, v63, v31
	global_load_dword v119, v6, s[0:1] nt
	s_add_u32 s0, s0, 0x9000
	s_addc_u32 s1, s1, 0
	v_mov_b32_e32 v28, s3
	ds_read_b128 v[8:11], v28
	ds_read_b128 v[12:15], v28 offset:16
	ds_read_b128 v[16:19], v28 offset:4096
	ds_read_b128 v[20:23], v28 offset:4112
	ds_read_b128 v[24:27], v28 offset:8192
	ds_read_b128 v[28:31], v28 offset:8208
	s_add_i32 s3, s3, 32
	s_waitcnt lgkmcnt(0)
	s_waitcnt vmcnt(55)
	v_fmac_f32_e32 v1, v64, v8
	v_fmac_f32_e32 v5, v64, v16
	v_fmac_f32_e32 v4, v64, v24
	global_load_dword v120, v6, s[0:1] nt
	s_add_u32 s0, s0, 0x9000
	s_addc_u32 s1, s1, 0
	s_waitcnt vmcnt(55)
	v_fmac_f32_e32 v1, v65, v9
	v_fmac_f32_e32 v5, v65, v17
	v_fmac_f32_e32 v4, v65, v25
	global_load_dword v121, v6, s[0:1] nt
	s_add_u32 s0, s0, 0x9000
	s_addc_u32 s1, s1, 0
	s_waitcnt vmcnt(55)
	v_fmac_f32_e32 v1, v66, v10
	v_fmac_f32_e32 v5, v66, v18
	v_fmac_f32_e32 v4, v66, v26
	global_load_dword v122, v6, s[0:1] nt
	s_add_u32 s0, s0, 0x9000
	s_addc_u32 s1, s1, 0
	s_waitcnt vmcnt(55)
	v_fmac_f32_e32 v1, v67, v11
	v_fmac_f32_e32 v5, v67, v19
	v_fmac_f32_e32 v4, v67, v27
	global_load_dword v123, v6, s[0:1] nt
	s_add_u32 s0, s0, 0x9000
	s_addc_u32 s1, s1, 0
	s_waitcnt vmcnt(55)
	v_fmac_f32_e32 v1, v68, v12
	v_fmac_f32_e32 v5, v68, v20
	v_fmac_f32_e32 v4, v68, v28
	global_load_dword v124, v6, s[0:1] nt
	s_add_u32 s0, s0, 0x9000
	s_addc_u32 s1, s1, 0
	s_waitcnt vmcnt(55)
	v_fmac_f32_e32 v1, v69, v13
	v_fmac_f32_e32 v5, v69, v21
	v_fmac_f32_e32 v4, v69, v29
	global_load_dword v125, v6, s[0:1] nt
	s_add_u32 s0, s0, 0x9000
	s_addc_u32 s1, s1, 0
	s_waitcnt vmcnt(55)
	v_fmac_f32_e32 v1, v70, v14
	v_fmac_f32_e32 v5, v70, v22
	v_fmac_f32_e32 v4, v70, v30
	global_load_dword v126, v6, s[0:1] nt
	s_add_u32 s0, s0, 0x9000
	s_addc_u32 s1, s1, 0
	s_waitcnt vmcnt(55)
	v_fmac_f32_e32 v1, v71, v15
	v_fmac_f32_e32 v5, v71, v23
	v_fmac_f32_e32 v4, v71, v31
	global_load_dword v127, v6, s[0:1] nt
	s_add_u32 s0, s0, 0x9000
	s_addc_u32 s1, s1, 0
	v_mov_b32_e32 v28, s3
	ds_read_b128 v[8:11], v28
	ds_read_b128 v[12:15], v28 offset:16
	ds_read_b128 v[16:19], v28 offset:4096
	ds_read_b128 v[20:23], v28 offset:4112
	ds_read_b128 v[24:27], v28 offset:8192
	ds_read_b128 v[28:31], v28 offset:8208
	s_add_i32 s3, s3, 32
	s_waitcnt lgkmcnt(0)
	s_waitcnt vmcnt(55)
; __global__ void __launch_bounds__(NTHREADS) fwd_megakernel(Args a) {
;     ...
;         if (act) {
; #pragma unroll 8
;         for (int kk = 0; kk < 128; ++kk) { const float w = __builtin_nontemporal_load(a.w_mod + (size_t)(kb + kk) * NMOD + j); s0 += sil[kb + kk] * w; s1 += sil[1024 + kb + kk] * w; s2 += sil[2048 + kb + kk] * w; }
;         }
	v_fmac_f32_e32 v1, v72, v8
	v_fmac_f32_e32 v5, v72, v16
	v_fmac_f32_e32 v4, v72, v24
	global_load_dword v128, v6, s[0:1] nt
	s_add_u32 s0, s0, 0x9000
	s_addc_u32 s1, s1, 0
	s_waitcnt vmcnt(55)
	v_fmac_f32_e32 v1, v73, v9
	v_fmac_f32_e32 v5, v73, v17
	v_fmac_f32_e32 v4, v73, v25
	global_load_dword v129, v6, s[0:1] nt
	s_add_u32 s0, s0, 0x9000
	s_addc_u32 s1, s1, 0
	s_waitcnt vmcnt(55)
	v_fmac_f32_e32 v1, v74, v10
	v_fmac_f32_e32 v5, v74, v18
	v_fmac_f32_e32 v4, v74, v26
	global_load_dword v130, v6, s[0:1] nt
	s_add_u32 s0, s0, 0x9000
	s_addc_u32 s1, s1, 0
	s_waitcnt vmcnt(55)
	v_fmac_f32_e32 v1, v75, v11
	v_fmac_f32_e32 v5, v75, v19
	v_fmac_f32_e32 v4, v75, v27
	global_load_dword v131, v6, s[0:1] nt
	s_add_u32 s0, s0, 0x9000
	s_addc_u32 s1, s1, 0
	s_waitcnt vmcnt(55)
	v_fmac_f32_e32 v1, v76, v12
	v_fmac_f32_e32 v5, v76, v20
	v_fmac_f32_e32 v4, v76, v28
	global_load_dword v132, v6, s[0:1] nt
	s_add_u32 s0, s0, 0x9000
	s_addc_u32 s1, s1, 0
	s_waitcnt vmcnt(55)
	v_fmac_f32_e32 v1, v77, v13
	v_fmac_f32_e32 v5, v77, v21
	v_fmac_f32_e32 v4, v77, v29
	global_load_dword v133, v6, s[0:1] nt
	s_add_u32 s0, s0, 0x9000
	s_addc_u32 s1, s1, 0
	s_waitcnt vmcnt(55)
	v_fmac_f32_e32 v1, v78, v14
	v_fmac_f32_e32 v5, v78, v22
	v_fmac_f32_e32 v4, v78, v30
	global_load_dword v134, v6, s[0:1] nt
	s_add_u32 s0, s0, 0x9000
	s_addc_u32 s1, s1, 0
	s_waitcnt vmcnt(55)
	v_fmac_f32_e32 v1, v79, v15
	v_fmac_f32_e32 v5, v79, v23
	v_fmac_f32_e32 v4, v79, v31
	global_load_dword v135, v6, s[0:1] nt
	s_add_u32 s0, s0, 0x9000
	s_addc_u32 s1, s1, 0
	v_mov_b32_e32 v28, s3
	ds_read_b128 v[8:11], v28
	ds_read_b128 v[12:15], v28 offset:16
	ds_read_b128 v[16:19], v28 offset:4096
	ds_read_b128 v[20:23], v28 offset:4112
	ds_read_b128 v[24:27], v28 offset:8192
	ds_read_b128 v[28:31], v28 offset:8208
	s_add_i32 s3, s3, 32
	s_waitcnt lgkmcnt(0)
	s_waitcnt vmcnt(55)
	v_fmac_f32_e32 v1, v80, v8
	v_fmac_f32_e32 v5, v80, v16
	v_fmac_f32_e32 v4, v80, v24
	global_load_dword v136, v6, s[0:1] nt
	s_add_u32 s0, s0, 0x9000
	s_addc_u32 s1, s1, 0
	s_waitcnt vmcnt(55)
	v_fmac_f32_e32 v1, v81, v9
	v_fmac_f32_e32 v5, v81, v17
	v_fmac_f32_e32 v4, v81, v25
	global_load_dword v137, v6, s[0:1] nt
	s_add_u32 s0, s0, 0x9000
	s_addc_u32 s1, s1, 0
	s_waitcnt vmcnt(55)
	v_fmac_f32_e32 v1, v82, v10
	v_fmac_f32_e32 v5, v82, v18
	v_fmac_f32_e32 v4, v82, v26
	global_load_dword v138, v6, s[0:1] nt
	s_add_u32 s0, s0, 0x9000
	s_addc_u32 s1, s1, 0
	s_waitcnt vmcnt(55)
	v_fmac_f32_e32 v1, v83, v11
	v_fmac_f32_e32 v5, v83, v19
	v_fmac_f32_e32 v4, v83, v27
	global_load_dword v139, v6, s[0:1] nt
	s_add_u32 s0, s0, 0x9000
	s_addc_u32 s1, s1, 0
	s_waitcnt vmcnt(55)
	v_fmac_f32_e32 v1, v84, v12
	v_fmac_f32_e32 v5, v84, v20
	v_fmac_f32_e32 v4, v84, v28
	global_load_dword v140, v6, s[0:1] nt
	s_add_u32 s0, s0, 0x9000
	s_addc_u32 s1, s1, 0
	s_waitcnt vmcnt(55)
	v_fmac_f32_e32 v1, v85, v13
	v_fmac_f32_e32 v5, v85, v21
	v_fmac_f32_e32 v4, v85, v29
	global_load_dword v141, v6, s[0:1] nt
	s_add_u32 s0, s0, 0x9000
	s_addc_u32 s1, s1, 0
	s_waitcnt vmcnt(55)
	v_fmac_f32_e32 v1, v86, v14
	v_fmac_f32_e32 v5, v86, v22
	v_fmac_f32_e32 v4, v86, v30
	global_load_dword v142, v6, s[0:1] nt
	s_add_u32 s0, s0, 0x9000
	s_addc_u32 s1, s1, 0
	s_waitcnt vmcnt(55)
	v_fmac_f32_e32 v1, v87, v15
	v_fmac_f32_e32 v5, v87, v23
	v_fmac_f32_e32 v4, v87, v31
	global_load_dword v143, v6, s[0:1] nt
	s_add_u32 s0, s0, 0x9000
	s_addc_u32 s1, s1, 0
	v_mov_b32_e32 v28, s3
	ds_read_b128 v[8:11], v28
	ds_read_b128 v[12:15], v28 offset:16
	ds_read_b128 v[16:19], v28 offset:4096
	ds_read_b128 v[20:23], v28 offset:4112
	ds_read_b128 v[24:27], v28 offset:8192
	ds_read_b128 v[28:31], v28 offset:8208
	s_add_i32 s3, s3, 32
	s_waitcnt lgkmcnt(0)
	s_waitcnt vmcnt(55)
	v_fmac_f32_e32 v1, v88, v8
	v_fmac_f32_e32 v5, v88, v16
	v_fmac_f32_e32 v4, v88, v24
	global_load_dword v144, v6, s[0:1] nt
	s_add_u32 s0, s0, 0x9000
	s_addc_u32 s1, s1, 0
	s_waitcnt vmcnt(55)
	v_fmac_f32_e32 v1, v89, v9
	v_fmac_f32_e32 v5, v89, v17
	v_fmac_f32_e32 v4, v89, v25
	global_load_dword v145, v6, s[0:1] nt
	s_add_u32 s0, s0, 0x9000
	s_addc_u32 s1, s1, 0
	s_waitcnt vmcnt(55)
	v_fmac_f32_e32 v1, v90, v10
	v_fmac_f32_e32 v5, v90, v18
	v_fmac_f32_e32 v4, v90, v26
	global_load_dword v146, v6, s[0:1] nt
	s_add_u32 s0, s0, 0x9000
	s_addc_u32 s1, s1, 0
	s_waitcnt vmcnt(55)
	v_fmac_f32_e32 v1, v91, v11
	v_fmac_f32_e32 v5, v91, v19
	v_fmac_f32_e32 v4, v91, v27
	global_load_dword v147, v6, s[0:1] nt
	s_add_u32 s0, s0, 0x9000
	s_addc_u32 s1, s1, 0
	s_waitcnt vmcnt(55)
	v_fmac_f32_e32 v1, v92, v12
	v_fmac_f32_e32 v5, v92, v20
	v_fmac_f32_e32 v4, v92, v28
	global_load_dword v148, v6, s[0:1] nt
	s_add_u32 s0, s0, 0x9000
	s_addc_u32 s1, s1, 0
	s_waitcnt vmcnt(55)
	v_fmac_f32_e32 v1, v93, v13
	v_fmac_f32_e32 v5, v93, v21
	v_fmac_f32_e32 v4, v93, v29
	global_load_dword v149, v6, s[0:1] nt
	s_add_u32 s0, s0, 0x9000
	s_addc_u32 s1, s1, 0
	s_waitcnt vmcnt(55)
	v_fmac_f32_e32 v1, v94, v14
	v_fmac_f32_e32 v5, v94, v22
	v_fmac_f32_e32 v4, v94, v30
	global_load_dword v150, v6, s[0:1] nt
	s_add_u32 s0, s0, 0x9000
	s_addc_u32 s1, s1, 0
	s_waitcnt vmcnt(55)
	v_fmac_f32_e32 v1, v95, v15
	v_fmac_f32_e32 v5, v95, v23
	v_fmac_f32_e32 v4, v95, v31
	global_load_dword v151, v6, s[0:1] nt
	s_add_u32 s0, s0, 0x9000
	s_addc_u32 s1, s1, 0
	v_mov_b32_e32 v28, s3
	ds_read_b128 v[8:11], v28
	ds_read_b128 v[12:15], v28 offset:16
	ds_read_b128 v[16:19], v28 offset:4096
	ds_read_b128 v[20:23], v28 offset:4112
	ds_read_b128 v[24:27], v28 offset:8192
	ds_read_b128 v[28:31], v28 offset:8208
	s_add_i32 s3, s3, 32
	s_waitcnt lgkmcnt(0)
	s_waitcnt vmcnt(55)
; __global__ void __launch_bounds__(NTHREADS) fwd_megakernel(Args a) {
;     ...
;         if (act) {
; #pragma unroll 8
;         for (int kk = 0; kk < 128; ++kk) { const float w = __builtin_nontemporal_load(a.w_mod + (size_t)(kb + kk) * NMOD + j); s0 += sil[kb + kk] * w; s1 += sil[1024 + kb + kk] * w; s2 += sil[2048 + kb + kk] * w; }
;         }
	v_fmac_f32_e32 v1, v96, v8
	v_fmac_f32_e32 v5, v96, v16
	v_fmac_f32_e32 v4, v96, v24
	global_load_dword v152, v6, s[0:1] nt
	s_add_u32 s0, s0, 0x9000
	s_addc_u32 s1, s1, 0
	s_waitcnt vmcnt(55)
	v_fmac_f32_e32 v1, v97, v9
	v_fmac_f32_e32 v5, v97, v17
	v_fmac_f32_e32 v4, v97, v25
	global_load_dword v153, v6, s[0:1] nt
	s_add_u32 s0, s0, 0x9000
	s_addc_u32 s1, s1, 0
	s_waitcnt vmcnt(55)
	v_fmac_f32_e32 v1, v98, v10
	v_fmac_f32_e32 v5, v98, v18
	v_fmac_f32_e32 v4, v98, v26
	global_load_dword v154, v6, s[0:1] nt
	s_add_u32 s0, s0, 0x9000
	s_addc_u32 s1, s1, 0
	s_waitcnt vmcnt(55)
	v_fmac_f32_e32 v1, v99, v11
	v_fmac_f32_e32 v5, v99, v19
	v_fmac_f32_e32 v4, v99, v27
	global_load_dword v155, v6, s[0:1] nt
	s_add_u32 s0, s0, 0x9000
	s_addc_u32 s1, s1, 0
	s_waitcnt vmcnt(55)
	v_fmac_f32_e32 v1, v100, v12
	v_fmac_f32_e32 v5, v100, v20
	v_fmac_f32_e32 v4, v100, v28
	global_load_dword v156, v6, s[0:1] nt
	s_add_u32 s0, s0, 0x9000
	s_addc_u32 s1, s1, 0
	s_waitcnt vmcnt(55)
	v_fmac_f32_e32 v1, v101, v13
	v_fmac_f32_e32 v5, v101, v21
	v_fmac_f32_e32 v4, v101, v29
	global_load_dword v157, v6, s[0:1] nt
	s_add_u32 s0, s0, 0x9000
	s_addc_u32 s1, s1, 0
	s_waitcnt vmcnt(55)
	v_fmac_f32_e32 v1, v102, v14
	v_fmac_f32_e32 v5, v102, v22
	v_fmac_f32_e32 v4, v102, v30
	global_load_dword v158, v6, s[0:1] nt
	s_add_u32 s0, s0, 0x9000
	s_addc_u32 s1, s1, 0
	s_waitcnt vmcnt(55)
	v_fmac_f32_e32 v1, v103, v15
	v_fmac_f32_e32 v5, v103, v23
	v_fmac_f32_e32 v4, v103, v31
	global_load_dword v159, v6, s[0:1] nt
	v_mov_b32_e32 v28, s3
	ds_read_b128 v[8:11], v28
	ds_read_b128 v[12:15], v28 offset:16
	ds_read_b128 v[16:19], v28 offset:4096
	ds_read_b128 v[20:23], v28 offset:4112
	ds_read_b128 v[24:27], v28 offset:8192
	ds_read_b128 v[28:31], v28 offset:8208
	s_add_i32 s3, s3, 32
	s_waitcnt lgkmcnt(0)
	s_waitcnt vmcnt(55)
	v_fmac_f32_e32 v1, v104, v8
	v_fmac_f32_e32 v5, v104, v16
	v_fmac_f32_e32 v4, v104, v24
	s_waitcnt vmcnt(54)
	v_fmac_f32_e32 v1, v105, v9
	v_fmac_f32_e32 v5, v105, v17
	v_fmac_f32_e32 v4, v105, v25
	s_waitcnt vmcnt(53)
	v_fmac_f32_e32 v1, v106, v10
	v_fmac_f32_e32 v5, v106, v18
	v_fmac_f32_e32 v4, v106, v26
	s_waitcnt vmcnt(52)
	v_fmac_f32_e32 v1, v107, v11
	v_fmac_f32_e32 v5, v107, v19
	v_fmac_f32_e32 v4, v107, v27
	s_waitcnt vmcnt(51)
	v_fmac_f32_e32 v1, v108, v12
	v_fmac_f32_e32 v5, v108, v20
	v_fmac_f32_e32 v4, v108, v28
	s_waitcnt vmcnt(50)
	v_fmac_f32_e32 v1, v109, v13
	v_fmac_f32_e32 v5, v109, v21
	v_fmac_f32_e32 v4, v109, v29
	s_waitcnt vmcnt(49)
	v_fmac_f32_e32 v1, v110, v14
	v_fmac_f32_e32 v5, v110, v22
	v_fmac_f32_e32 v4, v110, v30
	s_waitcnt vmcnt(48)
	v_fmac_f32_e32 v1, v111, v15
	v_fmac_f32_e32 v5, v111, v23
	v_fmac_f32_e32 v4, v111, v31
	v_mov_b32_e32 v28, s3
	ds_read_b128 v[8:11], v28
	ds_read_b128 v[12:15], v28 offset:16
	ds_read_b128 v[16:19], v28 offset:4096
	ds_read_b128 v[20:23], v28 offset:4112
	ds_read_b128 v[24:27], v28 offset:8192
	ds_read_b128 v[28:31], v28 offset:8208
	s_add_i32 s3, s3, 32
	s_waitcnt lgkmcnt(0)
	s_waitcnt vmcnt(47)
	v_fmac_f32_e32 v1, v112, v8
	v_fmac_f32_e32 v5, v112, v16
	v_fmac_f32_e32 v4, v112, v24
	s_waitcnt vmcnt(46)
	v_fmac_f32_e32 v1, v113, v9
	v_fmac_f32_e32 v5, v113, v17
	v_fmac_f32_e32 v4, v113, v25
	s_waitcnt vmcnt(45)
	v_fmac_f32_e32 v1, v114, v10
	v_fmac_f32_e32 v5, v114, v18
	v_fmac_f32_e32 v4, v114, v26
	s_waitcnt vmcnt(44)
	v_fmac_f32_e32 v1, v115, v11
	v_fmac_f32_e32 v5, v115, v19
	v_fmac_f32_e32 v4, v115, v27
	s_waitcnt vmcnt(43)
	v_fmac_f32_e32 v1, v116, v12
	v_fmac_f32_e32 v5, v116, v20
	v_fmac_f32_e32 v4, v116, v28
	s_waitcnt vmcnt(42)
	v_fmac_f32_e32 v1, v117, v13
	v_fmac_f32_e32 v5, v117, v21
	v_fmac_f32_e32 v4, v117, v29
	s_waitcnt vmcnt(41)
	v_fmac_f32_e32 v1, v118, v14
	v_fmac_f32_e32 v5, v118, v22
	v_fmac_f32_e32 v4, v118, v30
	s_waitcnt vmcnt(40)
	v_fmac_f32_e32 v1, v119, v15
	v_fmac_f32_e32 v5, v119, v23
	v_fmac_f32_e32 v4, v119, v31
	v_mov_b32_e32 v28, s3
	ds_read_b128 v[8:11], v28
	ds_read_b128 v[12:15], v28 offset:16
	ds_read_b128 v[16:19], v28 offset:4096
	ds_read_b128 v[20:23], v28 offset:4112
	ds_read_b128 v[24:27], v28 offset:8192
	ds_read_b128 v[28:31], v28 offset:8208
	s_add_i32 s3, s3, 32
	s_waitcnt lgkmcnt(0)
	s_waitcnt vmcnt(39)
	v_fmac_f32_e32 v1, v120, v8
	v_fmac_f32_e32 v5, v120, v16
	v_fmac_f32_e32 v4, v120, v24
	s_waitcnt vmcnt(38)
	v_fmac_f32_e32 v1, v121, v9
	v_fmac_f32_e32 v5, v121, v17
	v_fmac_f32_e32 v4, v121, v25
	s_waitcnt vmcnt(37)
	v_fmac_f32_e32 v1, v122, v10
	v_fmac_f32_e32 v5, v122, v18
	v_fmac_f32_e32 v4, v122, v26
	s_waitcnt vmcnt(36)
	v_fmac_f32_e32 v1, v123, v11
	v_fmac_f32_e32 v5, v123, v19
	v_fmac_f32_e32 v4, v123, v27
	s_waitcnt vmcnt(35)
	v_fmac_f32_e32 v1, v124, v12
	v_fmac_f32_e32 v5, v124, v20
	v_fmac_f32_e32 v4, v124, v28
	s_waitcnt vmcnt(34)
	v_fmac_f32_e32 v1, v125, v13
	v_fmac_f32_e32 v5, v125, v21
	v_fmac_f32_e32 v4, v125, v29
	s_waitcnt vmcnt(33)
; __global__ void __launch_bounds__(NTHREADS) fwd_megakernel(Args a) {
;     ...
;         if (act) {
; #pragma unroll 8
;         for (int kk = 0; kk < 128; ++kk) { const float w = __builtin_nontemporal_load(a.w_mod + (size_t)(kb + kk) * NMOD + j); s0 += sil[kb + kk] * w; s1 += sil[1024 + kb + kk] * w; s2 += sil[2048 + kb + kk] * w; }
;         }
	v_fmac_f32_e32 v1, v126, v14
	v_fmac_f32_e32 v5, v126, v22
	v_fmac_f32_e32 v4, v126, v30
	s_waitcnt vmcnt(32)
	v_fmac_f32_e32 v1, v127, v15
	v_fmac_f32_e32 v5, v127, v23
	v_fmac_f32_e32 v4, v127, v31
	v_mov_b32_e32 v28, s3
	ds_read_b128 v[8:11], v28
	ds_read_b128 v[12:15], v28 offset:16
	ds_read_b128 v[16:19], v28 offset:4096
	ds_read_b128 v[20:23], v28 offset:4112
	ds_read_b128 v[24:27], v28 offset:8192
	ds_read_b128 v[28:31], v28 offset:8208
	s_add_i32 s3, s3, 32
	s_waitcnt lgkmcnt(0)
	s_waitcnt vmcnt(31)
	v_fmac_f32_e32 v1, v128, v8
	v_fmac_f32_e32 v5, v128, v16
	v_fmac_f32_e32 v4, v128, v24
	s_waitcnt vmcnt(30)
	v_fmac_f32_e32 v1, v129, v9
	v_fmac_f32_e32 v5, v129, v17
	v_fmac_f32_e32 v4, v129, v25
	s_waitcnt vmcnt(29)
	v_fmac_f32_e32 v1, v130, v10
	v_fmac_f32_e32 v5, v130, v18
	v_fmac_f32_e32 v4, v130, v26
	s_waitcnt vmcnt(28)
	v_fmac_f32_e32 v1, v131, v11
	v_fmac_f32_e32 v5, v131, v19
	v_fmac_f32_e32 v4, v131, v27
	s_waitcnt vmcnt(27)
	v_fmac_f32_e32 v1, v132, v12
	v_fmac_f32_e32 v5, v132, v20
	v_fmac_f32_e32 v4, v132, v28
	s_waitcnt vmcnt(26)
	v_fmac_f32_e32 v1, v133, v13
	v_fmac_f32_e32 v5, v133, v21
	v_fmac_f32_e32 v4, v133, v29
	s_waitcnt vmcnt(25)
	v_fmac_f32_e32 v1, v134, v14
	v_fmac_f32_e32 v5, v134, v22
	v_fmac_f32_e32 v4, v134, v30
	s_waitcnt vmcnt(24)
	v_fmac_f32_e32 v1, v135, v15
	v_fmac_f32_e32 v5, v135, v23
	v_fmac_f32_e32 v4, v135, v31
	v_mov_b32_e32 v28, s3
	ds_read_b128 v[8:11], v28
	ds_read_b128 v[12:15], v28 offset:16
	ds_read_b128 v[16:19], v28 offset:4096
	ds_read_b128 v[20:23], v28 offset:4112
	ds_read_b128 v[24:27], v28 offset:8192
	ds_read_b128 v[28:31], v28 offset:8208
	s_add_i32 s3, s3, 32
	s_waitcnt lgkmcnt(0)
	s_waitcnt vmcnt(23)
	v_fmac_f32_e32 v1, v136, v8
	v_fmac_f32_e32 v5, v136, v16
	v_fmac_f32_e32 v4, v136, v24
	s_waitcnt vmcnt(22)
	v_fmac_f32_e32 v1, v137, v9
	v_fmac_f32_e32 v5, v137, v17
	v_fmac_f32_e32 v4, v137, v25
	s_waitcnt vmcnt(21)
	v_fmac_f32_e32 v1, v138, v10
	v_fmac_f32_e32 v5, v138, v18
	v_fmac_f32_e32 v4, v138, v26
	s_waitcnt vmcnt(20)
	v_fmac_f32_e32 v1, v139, v11
	v_fmac_f32_e32 v5, v139, v19
	v_fmac_f32_e32 v4, v139, v27
	s_waitcnt vmcnt(19)
	v_fmac_f32_e32 v1, v140, v12
	v_fmac_f32_e32 v5, v140, v20
	v_fmac_f32_e32 v4, v140, v28
	s_waitcnt vmcnt(18)
	v_fmac_f32_e32 v1, v141, v13
	v_fmac_f32_e32 v5, v141, v21
	v_fmac_f32_e32 v4, v141, v29
	s_waitcnt vmcnt(17)
	v_fmac_f32_e32 v1, v142, v14
	v_fmac_f32_e32 v5, v142, v22
	v_fmac_f32_e32 v4, v142, v30
	s_waitcnt vmcnt(16)
	v_fmac_f32_e32 v1, v143, v15
	v_fmac_f32_e32 v5, v143, v23
	v_fmac_f32_e32 v4, v143, v31
	v_mov_b32_e32 v28, s3
	ds_read_b128 v[8:11], v28
	ds_read_b128 v[12:15], v28 offset:16
	ds_read_b128 v[16:19], v28 offset:4096
	ds_read_b128 v[20:23], v28 offset:4112
	ds_read_b128 v[24:27], v28 offset:8192
	ds_read_b128 v[28:31], v28 offset:8208
	s_add_i32 s3, s3, 32
	s_waitcnt lgkmcnt(0)
	s_waitcnt vmcnt(15)
	v_fmac_f32_e32 v1, v144, v8
	v_fmac_f32_e32 v5, v144, v16
	v_fmac_f32_e32 v4, v144, v24
	s_waitcnt vmcnt(14)
	v_fmac_f32_e32 v1, v145, v9
	v_fmac_f32_e32 v5, v145, v17
	v_fmac_f32_e32 v4, v145, v25
	s_waitcnt vmcnt(13)
	v_fmac_f32_e32 v1, v146, v10
	v_fmac_f32_e32 v5, v146, v18
	v_fmac_f32_e32 v4, v146, v26
	s_waitcnt vmcnt(12)
	v_fmac_f32_e32 v1, v147, v11
	v_fmac_f32_e32 v5, v147, v19
	v_fmac_f32_e32 v4, v147, v27
	s_waitcnt vmcnt(11)
	v_fmac_f32_e32 v1, v148, v12
	v_fmac_f32_e32 v5, v148, v20
	v_fmac_f32_e32 v4, v148, v28
	s_waitcnt vmcnt(10)
	v_fmac_f32_e32 v1, v149, v13
	v_fmac_f32_e32 v5, v149, v21
	v_fmac_f32_e32 v4, v149, v29
	s_waitcnt vmcnt(9)
	v_fmac_f32_e32 v1, v150, v14
	v_fmac_f32_e32 v5, v150, v22
	v_fmac_f32_e32 v4, v150, v30
	s_waitcnt vmcnt(8)
	v_fmac_f32_e32 v1, v151, v15
	v_fmac_f32_e32 v5, v151, v23
	v_fmac_f32_e32 v4, v151, v31
	v_mov_b32_e32 v28, s3
	ds_read_b128 v[8:11], v28
	ds_read_b128 v[12:15], v28 offset:16
	ds_read_b128 v[16:19], v28 offset:4096
	ds_read_b128 v[20:23], v28 offset:4112
	ds_read_b128 v[24:27], v28 offset:8192
	ds_read_b128 v[28:31], v28 offset:8208
	s_waitcnt lgkmcnt(0)
	s_waitcnt vmcnt(7)
	v_fmac_f32_e32 v1, v152, v8
	v_fmac_f32_e32 v5, v152, v16
	v_fmac_f32_e32 v4, v152, v24
	s_waitcnt vmcnt(6)
	v_fmac_f32_e32 v1, v153, v9
	v_fmac_f32_e32 v5, v153, v17
	v_fmac_f32_e32 v4, v153, v25
	s_waitcnt vmcnt(5)
	v_fmac_f32_e32 v1, v154, v10
	v_fmac_f32_e32 v5, v154, v18
	v_fmac_f32_e32 v4, v154, v26
	s_waitcnt vmcnt(4)
	v_fmac_f32_e32 v1, v155, v11
	v_fmac_f32_e32 v5, v155, v19
	v_fmac_f32_e32 v4, v155, v27
	s_waitcnt vmcnt(3)
	v_fmac_f32_e32 v1, v156, v12
	v_fmac_f32_e32 v5, v156, v20
	v_fmac_f32_e32 v4, v156, v28
	s_waitcnt vmcnt(2)
	v_fmac_f32_e32 v1, v157, v13
	v_fmac_f32_e32 v5, v157, v21
	v_fmac_f32_e32 v4, v157, v29
	s_waitcnt vmcnt(1)
	v_fmac_f32_e32 v1, v158, v14
	v_fmac_f32_e32 v5, v158, v22
	v_fmac_f32_e32 v4, v158, v30
	s_waitcnt vmcnt(0)
	v_fmac_f32_e32 v1, v159, v15
	v_fmac_f32_e32 v5, v159, v23
	v_fmac_f32_e32 v4, v159, v31

;     __device__ bool next(int i, Unit& u) const { return map((long)i * G + c, u); }
; #define PG8_WAIT_V(n) asm volatile("s_waitcnt vmcnt(" #n ")" ::: "memory")
; #define PG8_BAR __builtin_amdgcn_s_barrier()
; template <class Epi, class Sched, bool ALIGN_EPI = true, bool SP2 = true>
; __device__ __forceinline__ void gemm_phase(LAS unsigned char* lds, const Gemm g, const Sched& S, const Epi& E) {
;     ...
;     unsigned voffA[2], voffB[2];
; #pragma unroll
;     for (int i = 0; i < 2; ++i) { int R, C; stage_rc(tid * 16 + i * 8192, R, C); const int Rb = Epi::PERM ? ((R & ~31) + perm32(R & 31)) : R;
;         voffA[i] = (unsigned)(R * K + C) * 2u; voffB[i] = (unsigned)(Rb * K + C) * 2u; }
;     const size_t kstep = (size_t)(BK * 2);
;     const size_t hstep = (size_t)HALF * K * 2;
;     const size_t tstep = 2 * hstep;
;     const unsigned ldsw = (unsigned)wid * 1024u;
;     const int aoff = lds_byte(wr * 64 + fr, fq * 8), boff = lds_byte(wc * 32 + fr, fq * 8);
;     ...
;     Unit cur, nxt; int ui = 0;
;     if (!S.next(0, cur)) return;
;     f32x4 acc[2][2][4][2];
; #pragma unroll
;     for (int a = 0; a < 2; ++a)
; #pragma unroll
;         for (int b = 0; b < 2; ++b)
; #pragma unroll
;             for (int m = 0; m < 4; ++m)
; #pragma unroll
;                 for (int n = 0; n < 2; ++n) acc[a][b][m][n] = (f32x4){0.f, 0.f, 0.f, 0.f};
;     bf16x8 At[4][2], B0[2][2], B1[2][2];
;     const char* cA = (const char*)g.A + (size_t)cur.pm * tstep; const char* cB = (const char*)g.Bt + (size_t)cur.pn * tstep;
;     if constexpr (SP2) {
;         PG8_STAGE(PG8_SB(0, 0), cB, voffB); PG8_STAGE(PG8_SB(0, 1), cB + hstep, voffB); PG8_STAGE(PG8_SA(0, 0), cA, voffA); PG8_STAGE(PG8_SA(0, 1), cA + hstep, voffA);
;         if (wr == 1) PG8_BAR;
;         PG8_WAIT_V(2); PG8_BAR;
;         PG8_STAGE(PG8_SB(1, 0), cB + kstep, voffB); PG8_STAGE(PG8_SA(1, 0), cA + kstep, voffA); PG8_STAGE(PG8_SB(1, 1), cB + hstep + kstep, voffB);
;         PG8_WAIT_V(6); PG8_BAR;
;     } else {
;         PG8_STAGE(PG8_SB(0, 0), cB, voffB); PG8_STAGE(PG8_SA(0, 0), cA, voffA); PG8_STAGE(PG8_SB(0, 1), cB + hstep, voffB); PG8_STAGE(PG8_SA(0, 1), cA + hstep, voffA);
;         if (wr == 1) PG8_BAR;
;         PG8_WAIT_V(4); PG8_BAR;
;         PG8_STAGE(PG8_SB(1, 0), cB + kstep, voffB); PG8_STAGE(PG8_SA(1, 0), cA + kstep, voffA); PG8_STAGE(PG8_SB(1, 1), cB + hstep + kstep, voffB);
;         PG8_WAIT_V(6); PG8_BAR;
;     }
.LBB0_243:
	v_lshrrev_b32_e32 v16, 1, v11
	v_and_b32_e32 v142, 24, v16
	s_lshl_b32 s12, s12, 5
	v_and_b32_e32 v15, 15, v11
	v_lshlrev_b32_e32 v16, 1, v142
	v_lshlrev_b32_e32 v11, 2, v11
	s_and_b32 s39, s12, 0x60
	v_lshl_or_b32 v129, s13, 6, v15
	v_lshl_or_b32 v15, v15, 6, v16
	s_lshl_b32 s13, s13, 13
	v_and_b32_e32 v11, 32, v11
	s_lshl_b32 s12, s39, 7
	v_bitop3_b32 v16, v15, s13, v11 bitop3:0xde
	v_bitop3_b32 v11, v15, s12, v11 bitop3:0xde
	s_mov_b64 s[12:13], 0x80
	s_add_i32 m0, s25, 0x18000
	v_lshl_add_u64 v[6:7], v[6:7], 0, s[12:13]
	s_waitcnt vmcnt(2)
	s_barrier
	global_load_lds_dwordx4 v[6:7], off
	v_lshl_add_u64 v[4:5], v[4:5], 0, s[12:13]
	s_add_i32 m0, s25, 0x1a000
	s_add_i32 s42, s25, 0x8000
	s_add_i32 s43, s25, 0xa000
	global_load_lds_dwordx4 v[4:5], off
	v_lshl_add_u64 v[2:3], v[2:3], 0, s[12:13]
	s_mov_b32 m0, s42
	s_add_u32 s48, s8, 0x40080
	global_load_lds_dwordx4 v[2:3], off
	v_lshl_add_u64 v[0:1], v[0:1], 0, s[12:13]
	s_mov_b32 m0, s43
	s_addc_u32 s49, s9, 0
	global_load_lds_dwordx4 v[0:1], off
	s_add_i32 m0, s25, 0x1c000
	v_lshl_add_u64 v[0:1], s[48:49], 0, v[134:135]
	global_load_lds_dwordx4 v[0:1], off
	v_lshl_add_u64 v[0:1], s[48:49], 0, v[130:131]
	s_add_i32 m0, s25, 0x1e000
	s_lshl_b32 s14, s14, 19
	global_load_lds_dwordx4 v[0:1], off
	v_lshlrev_b32_e32 v0, 14, v13
	v_and_b32_e32 v0, 0xffff8000, v0
	v_lshl_add_u32 v0, v12, 11, v0
	v_and_b32_e32 v1, 1, v13
	s_add_u32 s14, s30, s14
	v_lshl_or_b32 v0, v1, 6, v0
	s_addc_u32 s15, s31, 0
	v_lshl_add_u32 v0, v14, 1, v0
	v_mov_b32_e32 v1, v135
	v_lshl_add_u64 v[0:1], s[14:15], 0, v[0:1]
	s_mov_b64 s[48:49], 0x7a40080
	v_lshl_add_u64 v[138:139], v[0:1], 0, s[48:49]
	v_lshlrev_b32_e32 v0, 14, v8
	v_and_b32_e32 v0, 0xffff8000, v0
	s_add_u32 s44, s30, s44
	v_lshl_add_u32 v0, v9, 11, v0
	v_and_b32_e32 v1, 1, v8
	s_addc_u32 s45, s31, 0
	v_lshl_or_b32 v0, v1, 6, v0
	s_add_u32 s44, s44, 0x100100
	s_waitcnt vmcnt(6)
	v_lshl_add_u32 v0, v10, 1, v0
	v_mov_b32_e32 v1, v135
	s_addc_u32 s45, s45, 0
	s_add_i32 s69, 0, 0x10000
	s_add_i32 s71, 0, 0x14000
	s_add_i32 s73, 0, 0x18000
	s_add_i32 s79, 0, 0x1c000
	v_lshl_add_u64 v[0:1], s[14:15], 0, v[0:1]
	v_add_u32_e32 v143, s69, v11
	v_add_u32_e32 v144, s71, v11
	s_add_i32 s69, s69, s60
	s_add_i32 s71, s71, s60
	v_add_u32_e32 v146, s73, v11
	v_add_u32_e32 v147, s79, v11
	s_add_i32 s73, s73, s60
	s_add_i32 s79, s79, s60
	v_lshl_add_u64 v[140:141], v[0:1], 0, s[48:49]
	s_mov_b32 s64, -2
	s_mov_b64 s[48:49], 0
	v_add_u32_e32 v145, 0, v16
	s_add_i32 s65, s25, 0xc000
	s_add_i32 s68, s25, 0xe000
	s_add_i32 s70, s69, 0x2000
	s_add_i32 s72, s71, 0x2000
	s_add_i32 s78, s73, 0x2000
	s_add_i32 s84, s79, 0x2000
	v_mov_b64_e32 v[0:1], 0
	v_mov_b64_e32 v[2:3], 0
	v_mov_b64_e32 v[4:5], 0
	v_mov_b64_e32 v[6:7], 0
	v_mov_b64_e32 v[16:17], 0
	v_mov_b64_e32 v[18:19], 0
	v_mov_b64_e32 v[20:21], 0
	v_mov_b64_e32 v[22:23], 0
	v_mov_b64_e32 v[32:33], 0
	v_mov_b64_e32 v[34:35], 0
	v_mov_b64_e32 v[36:37], 0
	v_mov_b64_e32 v[38:39], 0
	v_mov_b64_e32 v[48:49], 0
	v_mov_b64_e32 v[50:51], 0
	v_mov_b64_e32 v[52:53], 0
	v_mov_b64_e32 v[54:55], 0
	v_mov_b64_e32 v[8:9], 0
	v_mov_b64_e32 v[10:11], 0
	v_mov_b64_e32 v[12:13], 0
	v_mov_b64_e32 v[14:15], 0
	v_mov_b64_e32 v[24:25], 0
	v_mov_b64_e32 v[26:27], 0
	v_mov_b64_e32 v[28:29], 0
	v_mov_b64_e32 v[30:31], 0
	v_mov_b64_e32 v[40:41], 0
	v_mov_b64_e32 v[42:43], 0
	v_mov_b64_e32 v[44:45], 0
	v_mov_b64_e32 v[46:47], 0
	v_mov_b64_e32 v[56:57], 0
	v_mov_b64_e32 v[58:59], 0
	v_mov_b64_e32 v[60:61], 0
	v_mov_b64_e32 v[62:63], 0
	v_mov_b64_e32 v[64:65], 0
	v_mov_b64_e32 v[66:67], 0
	v_mov_b64_e32 v[68:69], 0
	v_mov_b64_e32 v[70:71], 0
	v_mov_b64_e32 v[80:81], 0
	v_mov_b64_e32 v[82:83], 0
	v_mov_b64_e32 v[84:85], 0
	v_mov_b64_e32 v[86:87], 0
	v_mov_b64_e32 v[96:97], 0
	v_mov_b64_e32 v[98:99], 0
	v_mov_b64_e32 v[100:101], 0
	v_mov_b64_e32 v[102:103], 0
	v_mov_b64_e32 v[112:113], 0
	v_mov_b64_e32 v[114:115], 0
	v_mov_b64_e32 v[116:117], 0
	v_mov_b64_e32 v[118:119], 0
	v_mov_b64_e32 v[72:73], 0
	v_mov_b64_e32 v[74:75], 0
	v_mov_b64_e32 v[76:77], 0
	v_mov_b64_e32 v[78:79], 0
	v_mov_b64_e32 v[88:89], 0
	v_mov_b64_e32 v[90:91], 0
	v_mov_b64_e32 v[92:93], 0
	v_mov_b64_e32 v[94:95], 0
	v_mov_b64_e32 v[104:105], 0
	v_mov_b64_e32 v[106:107], 0
	v_mov_b64_e32 v[108:109], 0
	v_mov_b64_e32 v[110:111], 0
	v_mov_b64_e32 v[120:121], 0
	v_mov_b64_e32 v[122:123], 0
	v_mov_b64_e32 v[124:125], 0
	v_mov_b64_e32 v[126:127], 0
	s_barrier

;     __device__ bool next(int i, Unit& u) const { return map((long)i * G + c, u); }
; template <class Epi, class Sched, bool ALIGN_EPI = true, bool SP2 = true>
; __device__ __forceinline__ void gemm_phase(LAS unsigned char* lds, const Gemm g, const Sched& S, const Epi& E) {
;     ...
;         const bool has_next = S.next(ui + 1, nxt);
;         const char* nA = has_next ? (const char*)g.A + (size_t)nxt.pm * tstep : cA; const char* nB = has_next ? (const char*)g.Bt + (size_t)nxt.pn * tstep : cB;
;     ...
; #pragma unroll
;         for (int a = 0; a < 2; ++a)
; #pragma unroll
;             for (int b = 0; b < 2; ++b)
; #pragma unroll
;                 for (int m = 0; m < 4; ++m)
; #pragma unroll
;                     for (int n = 0; n < 2; ++n) acc[a][b][m][n] = (f32x4){0.f, 0.f, 0.f, 0.f};
;         cur = nxt; cA = nA; cB = nB; ++ui;
.LBB0_270:
	s_ashr_i32 s65, s64, 31
	s_lshl_b64 s[72:73], s[64:65], 19
	s_add_u32 s72, s97, s72
	s_addc_u32 s73, s3, s73
	s_and_b64 s[78:79], s[70:71], exec
	s_cselect_b32 s65, s73, s91
	s_cselect_b32 s84, s72, s90
	s_ashr_i32 s69, s68, 31
	s_lshl_b64 s[78:79], s[68:69], 19
	s_add_u32 s78, s4, s78
	s_addc_u32 s79, s5, s79
	s_and_b64 s[94:95], s[70:71], exec
	s_cselect_b32 s69, s79, s93
	s_cselect_b32 s85, s78, s92
	s_add_u32 s90, s90, 0x40080
	s_addc_u32 s91, s91, 0
	s_add_u32 s89, s92, 0x100
	v_mov_b32_e32 v0, 0
	s_addc_u32 vcc_lo, s93, 0
	s_mov_b32 vcc_hi, -2
	v_mov_b32_e32 v1, v0
	v_mov_b64_e32 v[2:3], 0
	v_mov_b64_e32 v[4:5], 0
	v_mov_b64_e32 v[6:7], 0
	v_mov_b64_e32 v[16:17], 0
	v_mov_b64_e32 v[18:19], 0
	v_mov_b64_e32 v[20:21], 0
	v_mov_b64_e32 v[22:23], 0
	v_mov_b64_e32 v[32:33], 0
	v_mov_b64_e32 v[34:35], 0
	v_mov_b64_e32 v[36:37], 0
	v_mov_b64_e32 v[38:39], 0
	v_mov_b64_e32 v[48:49], 0
	v_mov_b64_e32 v[50:51], 0
	v_mov_b64_e32 v[52:53], 0
	v_mov_b64_e32 v[54:55], 0
	v_mov_b64_e32 v[8:9], 0
	v_mov_b64_e32 v[10:11], 0
	v_mov_b64_e32 v[12:13], 0
	v_mov_b64_e32 v[14:15], 0
	v_mov_b64_e32 v[24:25], 0
	v_mov_b64_e32 v[26:27], 0
	v_mov_b64_e32 v[28:29], 0
	v_mov_b64_e32 v[30:31], 0
	v_mov_b64_e32 v[40:41], 0
	v_mov_b64_e32 v[42:43], 0
	v_mov_b64_e32 v[44:45], 0
	v_mov_b64_e32 v[46:47], 0
	v_mov_b64_e32 v[56:57], 0
	v_mov_b64_e32 v[58:59], 0
	v_mov_b64_e32 v[60:61], 0
	v_mov_b64_e32 v[62:63], 0
	v_mov_b64_e32 v[64:65], 0
	v_mov_b64_e32 v[66:67], 0
	v_mov_b64_e32 v[68:69], 0
	v_mov_b64_e32 v[70:71], 0
	v_mov_b64_e32 v[80:81], 0
	v_mov_b64_e32 v[82:83], 0
	v_mov_b64_e32 v[84:85], 0
	v_mov_b64_e32 v[86:87], 0
	v_mov_b64_e32 v[96:97], 0
	v_mov_b64_e32 v[98:99], 0
	v_mov_b64_e32 v[100:101], 0
	v_mov_b64_e32 v[102:103], 0
	v_mov_b64_e32 v[112:113], 0
	v_mov_b64_e32 v[114:115], 0
	v_mov_b64_e32 v[116:117], 0
	v_mov_b64_e32 v[118:119], 0
	v_mov_b64_e32 v[72:73], 0
	v_mov_b64_e32 v[74:75], 0
	v_mov_b64_e32 v[76:77], 0
	v_mov_b64_e32 v[78:79], 0
	v_mov_b64_e32 v[88:89], 0
	v_mov_b64_e32 v[90:91], 0
	v_mov_b64_e32 v[92:93], 0
	v_mov_b64_e32 v[94:95], 0
	v_mov_b64_e32 v[104:105], 0
	v_mov_b64_e32 v[106:107], 0
	v_mov_b64_e32 v[108:109], 0
	v_mov_b64_e32 v[110:111], 0
	v_mov_b64_e32 v[120:121], 0
	v_mov_b64_e32 v[122:123], 0
	v_mov_b64_e32 v[124:125], 0
	v_mov_b64_e32 v[126:127], 0

;     __device__ bool next(int i, Unit& u) const { return map((long)i * G + c, u); }
; #define PG8_WAIT_V(n) asm volatile("s_waitcnt vmcnt(" #n ")" ::: "memory")
; #define PG8_BAR __builtin_amdgcn_s_barrier()
; template <class Epi, class Sched, bool ALIGN_EPI = true, bool SP2 = true>
; __device__ __forceinline__ void gemm_phase(LAS unsigned char* lds, const Gemm g, const Sched& S, const Epi& E) {
;     ...
;     unsigned voffA[2], voffB[2];
; #pragma unroll
;     for (int i = 0; i < 2; ++i) { int R, C; stage_rc(tid * 16 + i * 8192, R, C); const int Rb = Epi::PERM ? ((R & ~31) + perm32(R & 31)) : R;
;         voffA[i] = (unsigned)(R * K + C) * 2u; voffB[i] = (unsigned)(Rb * K + C) * 2u; }
;     const size_t kstep = (size_t)(BK * 2);
;     const size_t hstep = (size_t)HALF * K * 2;
;     const size_t tstep = 2 * hstep;
;     const unsigned ldsw = (unsigned)wid * 1024u;
;     const int aoff = lds_byte(wr * 64 + fr, fq * 8), boff = lds_byte(wc * 32 + fr, fq * 8);
;     ...
;     Unit cur, nxt; int ui = 0;
;     if (!S.next(0, cur)) return;
;     f32x4 acc[2][2][4][2];
; #pragma unroll
;     for (int a = 0; a < 2; ++a)
; #pragma unroll
;         for (int b = 0; b < 2; ++b)
; #pragma unroll
;             for (int m = 0; m < 4; ++m)
; #pragma unroll
;                 for (int n = 0; n < 2; ++n) acc[a][b][m][n] = (f32x4){0.f, 0.f, 0.f, 0.f};
;     bf16x8 At[4][2], B0[2][2], B1[2][2];
;     const char* cA = (const char*)g.A + (size_t)cur.pm * tstep; const char* cB = (const char*)g.Bt + (size_t)cur.pn * tstep;
;     if constexpr (SP2) {
;         PG8_STAGE(PG8_SB(0, 0), cB, voffB); PG8_STAGE(PG8_SB(0, 1), cB + hstep, voffB); PG8_STAGE(PG8_SA(0, 0), cA, voffA); PG8_STAGE(PG8_SA(0, 1), cA + hstep, voffA);
;         if (wr == 1) PG8_BAR;
;         PG8_WAIT_V(2); PG8_BAR;
;         PG8_STAGE(PG8_SB(1, 0), cB + kstep, voffB); PG8_STAGE(PG8_SA(1, 0), cA + kstep, voffA); PG8_STAGE(PG8_SB(1, 1), cB + hstep + kstep, voffB);
;         PG8_WAIT_V(6); PG8_BAR;
;     } else {
;         PG8_STAGE(PG8_SB(0, 0), cB, voffB); PG8_STAGE(PG8_SA(0, 0), cA, voffA); PG8_STAGE(PG8_SB(0, 1), cB + hstep, voffB); PG8_STAGE(PG8_SA(0, 1), cA + hstep, voffA);
;         if (wr == 1) PG8_BAR;
;         PG8_WAIT_V(4); PG8_BAR;
;         PG8_STAGE(PG8_SB(1, 0), cB + kstep, voffB); PG8_STAGE(PG8_SA(1, 0), cA + kstep, voffA); PG8_STAGE(PG8_SB(1, 1), cB + hstep + kstep, voffB);
;         PG8_WAIT_V(6); PG8_BAR;
;     }
.LBB0_284:
	v_lshrrev_b32_e32 v18, 1, v12
	v_and_b32_e32 v142, 24, v18
	s_lshl_b32 s10, s10, 5
	v_and_b32_e32 v17, 15, v12
	v_lshlrev_b32_e32 v18, 1, v142
	v_lshlrev_b32_e32 v12, 2, v12
	s_and_b32 s38, s10, 0x60
	v_lshl_or_b32 v129, s11, 6, v17
	v_lshl_or_b32 v17, v17, 6, v18
	s_lshl_b32 s11, s11, 13
	v_and_b32_e32 v12, 32, v12
	s_lshl_b32 s10, s38, 7
	v_bitop3_b32 v18, v17, s11, v12 bitop3:0xde
	v_bitop3_b32 v12, v17, s10, v12 bitop3:0xde
	s_mov_b64 s[10:11], 0x80
	s_add_i32 m0, s24, 0x18000
	v_lshl_add_u64 v[6:7], v[6:7], 0, s[10:11]
	s_waitcnt vmcnt(2)
	s_barrier
	global_load_lds_dwordx4 v[6:7], off
	v_lshl_add_u64 v[4:5], v[4:5], 0, s[10:11]
	s_add_i32 m0, s24, 0x1a000
	s_add_i32 s39, s24, 0x8000
	s_add_i32 s42, s24, 0xa000
	global_load_lds_dwordx4 v[4:5], off
	v_lshl_add_u64 v[2:3], v[2:3], 0, s[10:11]
	s_mov_b32 m0, s39
	s_add_u32 s44, s0, 0xb0080
	global_load_lds_dwordx4 v[2:3], off
	v_lshl_add_u64 v[0:1], v[0:1], 0, s[10:11]
	s_mov_b32 m0, s42
	s_addc_u32 s45, s1, 0
	global_load_lds_dwordx4 v[0:1], off
	s_add_i32 m0, s24, 0x1c000
	v_lshl_add_u64 v[0:1], s[44:45], 0, v[134:135]
	global_load_lds_dwordx4 v[0:1], off
	v_lshl_add_u64 v[0:1], s[44:45], 0, v[130:131]
	s_add_i32 m0, s24, 0x1e000
	s_mov_b32 s16, 0xb000
	global_load_lds_dwordx4 v[0:1], off
	v_lshrrev_b32_e32 v1, 1, v14
	v_mul_lo_u32 v0, v13, s14
	s_mul_hi_i32 s13, s12, 0x160000
	s_mul_i32 s12, s12, 0x160000
	v_mad_u64_u32 v[0:1], s[44:45], v1, s16, v[0:1]
	s_add_u32 s12, s30, s12
	v_or_b32_e32 v0, v0, v15
	s_addc_u32 s13, s31, s13
	v_add_lshl_u32 v0, v0, v16, 1
	v_mov_b32_e32 v1, v135
	v_lshl_add_u64 v[0:1], s[12:13], 0, v[0:1]
	s_mov_b64 s[44:45], 0xd3b0080
	v_lshl_add_u64 v[138:139], v[0:1], 0, s[44:45]
	v_lshrrev_b32_e32 v1, 1, v8
	v_mul_lo_u32 v0, v9, s14
	v_mad_u64_u32 v[0:1], s[46:47], v1, s16, v[0:1]
	v_or_b32_e32 v0, v0, v10
	s_add_u32 s14, s30, s15
	v_add_lshl_u32 v0, v0, v11, 1
	v_mov_b32_e32 v1, v135
	s_addc_u32 s15, s31, 0
	v_lshl_add_u64 v[0:1], s[12:13], 0, v[0:1]
	s_add_u32 s43, s14, 0xc00100
	s_waitcnt vmcnt(6)
	v_lshl_add_u64 v[140:141], v[0:1], 0, s[44:45]
	s_addc_u32 s44, s15, 0
	s_add_i32 s64, 0, 0x10000
	s_add_i32 s68, 0, 0x14000
	s_add_i32 s70, 0, 0x18000
	s_add_i32 s72, 0, 0x1c000
	v_add_u32_e32 v143, s64, v12
	v_add_u32_e32 v144, s68, v12
	s_add_i32 s64, s64, s60
	s_add_i32 s68, s68, s60
	v_add_u32_e32 v146, s70, v12
	v_add_u32_e32 v147, s72, v12
	s_add_i32 s70, s70, s60
	s_add_i32 s72, s72, s60
	s_mov_b32 s45, -2
	s_mov_b64 s[14:15], 0
	v_add_u32_e32 v145, 0, v18
	s_add_i32 s48, s24, 0xc000
	s_add_i32 s49, s24, 0xe000
	s_add_i32 s65, s64, 0x2000
	s_add_i32 s69, s68, 0x2000
	s_add_i32 s71, s70, 0x2000
	s_add_i32 s73, s72, 0x2000
	v_mov_b64_e32 v[0:1], 0
	v_mov_b64_e32 v[2:3], 0
	v_mov_b64_e32 v[4:5], 0
	v_mov_b64_e32 v[6:7], 0
	v_mov_b64_e32 v[8:9], 0
	v_mov_b64_e32 v[10:11], 0
	v_mov_b64_e32 v[12:13], 0
	v_mov_b64_e32 v[14:15], 0
	v_mov_b64_e32 v[24:25], 0
	v_mov_b64_e32 v[26:27], 0
	v_mov_b64_e32 v[28:29], 0
	v_mov_b64_e32 v[30:31], 0
	v_mov_b64_e32 v[40:41], 0
	v_mov_b64_e32 v[42:43], 0
	v_mov_b64_e32 v[44:45], 0
	v_mov_b64_e32 v[46:47], 0
	v_mov_b64_e32 v[16:17], 0
	v_mov_b64_e32 v[18:19], 0
	v_mov_b64_e32 v[20:21], 0
	v_mov_b64_e32 v[22:23], 0
	v_mov_b64_e32 v[32:33], 0
	v_mov_b64_e32 v[34:35], 0
	v_mov_b64_e32 v[36:37], 0
	v_mov_b64_e32 v[38:39], 0
	v_mov_b64_e32 v[48:49], 0
	v_mov_b64_e32 v[50:51], 0
	v_mov_b64_e32 v[52:53], 0
	v_mov_b64_e32 v[54:55], 0
	v_mov_b64_e32 v[56:57], 0
	v_mov_b64_e32 v[58:59], 0
	v_mov_b64_e32 v[60:61], 0
	v_mov_b64_e32 v[62:63], 0
	v_mov_b64_e32 v[64:65], 0
	v_mov_b64_e32 v[66:67], 0
	v_mov_b64_e32 v[68:69], 0
	v_mov_b64_e32 v[70:71], 0
	v_mov_b64_e32 v[72:73], 0
	v_mov_b64_e32 v[74:75], 0
	v_mov_b64_e32 v[76:77], 0
	v_mov_b64_e32 v[78:79], 0
	v_mov_b64_e32 v[88:89], 0
	v_mov_b64_e32 v[90:91], 0
	v_mov_b64_e32 v[92:93], 0
	v_mov_b64_e32 v[94:95], 0
	v_mov_b64_e32 v[104:105], 0
	v_mov_b64_e32 v[106:107], 0
	v_mov_b64_e32 v[108:109], 0
	v_mov_b64_e32 v[110:111], 0
	v_mov_b64_e32 v[80:81], 0
	v_mov_b64_e32 v[82:83], 0
	v_mov_b64_e32 v[84:85], 0
	v_mov_b64_e32 v[86:87], 0
	v_mov_b64_e32 v[96:97], 0
	v_mov_b64_e32 v[98:99], 0
	v_mov_b64_e32 v[100:101], 0
	v_mov_b64_e32 v[102:103], 0
	v_mov_b64_e32 v[112:113], 0
	v_mov_b64_e32 v[114:115], 0
	v_mov_b64_e32 v[116:117], 0
	v_mov_b64_e32 v[118:119], 0
	v_mov_b64_e32 v[120:121], 0
	v_mov_b64_e32 v[122:123], 0
	v_mov_b64_e32 v[124:125], 0
	v_mov_b64_e32 v[126:127], 0
	s_barrier

; template <class Epi, class Sched, bool ALIGN_EPI = true, bool SP2 = true>
; __device__ __forceinline__ void gemm_phase(LAS unsigned char* lds, const Gemm g, const Sched& S, const Epi& E) {
;     ...
; #pragma unroll
;         for (int a = 0; a < 2; ++a)
; #pragma unroll
;             for (int b = 0; b < 2; ++b)
; #pragma unroll
;                 for (int m = 0; m < 4; ++m)
; #pragma unroll
;                     for (int n = 0; n < 2; ++n) acc[a][b][m][n] = (f32x4){0.f, 0.f, 0.f, 0.f};
;         cur = nxt; cA = nA; cB = nB; ++ui;
.LBB0_363:
	s_add_u32 s61, s64, 0x100
	v_mov_b32_e32 v0, 0
	s_addc_u32 s72, s65, 0
	s_mov_b32 s73, -2
	v_mov_b32_e32 v1, v0
	v_mov_b64_e32 v[2:3], 0
	v_mov_b64_e32 v[4:5], 0
	v_mov_b64_e32 v[6:7], 0
	v_mov_b64_e32 v[8:9], 0
	v_mov_b64_e32 v[10:11], 0
	v_mov_b64_e32 v[12:13], 0
	v_mov_b64_e32 v[14:15], 0
	v_mov_b64_e32 v[24:25], 0
	v_mov_b64_e32 v[26:27], 0
	v_mov_b64_e32 v[28:29], 0
	v_mov_b64_e32 v[30:31], 0
	v_mov_b64_e32 v[40:41], 0
	v_mov_b64_e32 v[42:43], 0
	v_mov_b64_e32 v[44:45], 0
	v_mov_b64_e32 v[46:47], 0
	v_mov_b64_e32 v[16:17], 0
	v_mov_b64_e32 v[18:19], 0
	v_mov_b64_e32 v[20:21], 0
	v_mov_b64_e32 v[22:23], 0
	v_mov_b64_e32 v[32:33], 0
	v_mov_b64_e32 v[34:35], 0
	v_mov_b64_e32 v[36:37], 0
	v_mov_b64_e32 v[38:39], 0
	v_mov_b64_e32 v[48:49], 0
	v_mov_b64_e32 v[50:51], 0
	v_mov_b64_e32 v[52:53], 0
	v_mov_b64_e32 v[54:55], 0
	v_mov_b64_e32 v[56:57], 0
	v_mov_b64_e32 v[58:59], 0
	v_mov_b64_e32 v[60:61], 0
	v_mov_b64_e32 v[62:63], 0
	v_mov_b64_e32 v[64:65], 0
	v_mov_b64_e32 v[66:67], 0
	v_mov_b64_e32 v[68:69], 0
	v_mov_b64_e32 v[70:71], 0
	v_mov_b64_e32 v[72:73], 0
	v_mov_b64_e32 v[74:75], 0
	v_mov_b64_e32 v[76:77], 0
	v_mov_b64_e32 v[78:79], 0
	v_mov_b64_e32 v[88:89], 0
	v_mov_b64_e32 v[90:91], 0
	v_mov_b64_e32 v[92:93], 0
	v_mov_b64_e32 v[94:95], 0
	v_mov_b64_e32 v[104:105], 0
	v_mov_b64_e32 v[106:107], 0
	v_mov_b64_e32 v[108:109], 0
	v_mov_b64_e32 v[110:111], 0
	v_mov_b64_e32 v[80:81], 0
	v_mov_b64_e32 v[82:83], 0
	v_mov_b64_e32 v[84:85], 0
	v_mov_b64_e32 v[86:87], 0
	v_mov_b64_e32 v[96:97], 0
	v_mov_b64_e32 v[98:99], 0
	v_mov_b64_e32 v[100:101], 0
	v_mov_b64_e32 v[102:103], 0
	v_mov_b64_e32 v[112:113], 0
	v_mov_b64_e32 v[114:115], 0
	v_mov_b64_e32 v[116:117], 0
	v_mov_b64_e32 v[118:119], 0
	v_mov_b64_e32 v[120:121], 0
	v_mov_b64_e32 v[122:123], 0
	v_mov_b64_e32 v[124:125], 0
	v_mov_b64_e32 v[126:127], 0

;     __device__ bool next(int i, Unit& u) const { return map((long)i * G + c, u); }
; #define PG8_WAIT_V(n) asm volatile("s_waitcnt vmcnt(" #n ")" ::: "memory")
; #define PG8_BAR __builtin_amdgcn_s_barrier()
; template <class Epi, class Sched, bool ALIGN_EPI = true, bool SP2 = true>
; __device__ __forceinline__ void gemm_phase(LAS unsigned char* lds, const Gemm g, const Sched& S, const Epi& E) {
;     ...
;     unsigned voffA[2], voffB[2];
; #pragma unroll
;     for (int i = 0; i < 2; ++i) { int R, C; stage_rc(tid * 16 + i * 8192, R, C); const int Rb = Epi::PERM ? ((R & ~31) + perm32(R & 31)) : R;
;         voffA[i] = (unsigned)(R * K + C) * 2u; voffB[i] = (unsigned)(Rb * K + C) * 2u; }
;     const size_t kstep = (size_t)(BK * 2);
;     const size_t hstep = (size_t)HALF * K * 2;
;     const size_t tstep = 2 * hstep;
;     const unsigned ldsw = (unsigned)wid * 1024u;
;     const int aoff = lds_byte(wr * 64 + fr, fq * 8), boff = lds_byte(wc * 32 + fr, fq * 8);
;     ...
;     Unit cur, nxt; int ui = 0;
;     if (!S.next(0, cur)) return;
;     f32x4 acc[2][2][4][2];
; #pragma unroll
;     for (int a = 0; a < 2; ++a)
; #pragma unroll
;         for (int b = 0; b < 2; ++b)
; #pragma unroll
;             for (int m = 0; m < 4; ++m)
; #pragma unroll
;                 for (int n = 0; n < 2; ++n) acc[a][b][m][n] = (f32x4){0.f, 0.f, 0.f, 0.f};
;     bf16x8 At[4][2], B0[2][2], B1[2][2];
;     const char* cA = (const char*)g.A + (size_t)cur.pm * tstep; const char* cB = (const char*)g.Bt + (size_t)cur.pn * tstep;
;     if constexpr (SP2) {
;         PG8_STAGE(PG8_SB(0, 0), cB, voffB); PG8_STAGE(PG8_SB(0, 1), cB + hstep, voffB); PG8_STAGE(PG8_SA(0, 0), cA, voffA); PG8_STAGE(PG8_SA(0, 1), cA + hstep, voffA);
;         if (wr == 1) PG8_BAR;
;         PG8_WAIT_V(2); PG8_BAR;
;         PG8_STAGE(PG8_SB(1, 0), cB + kstep, voffB); PG8_STAGE(PG8_SA(1, 0), cA + kstep, voffA); PG8_STAGE(PG8_SB(1, 1), cB + hstep + kstep, voffB);
;         PG8_WAIT_V(6); PG8_BAR;
;     } else {
;         PG8_STAGE(PG8_SB(0, 0), cB, voffB); PG8_STAGE(PG8_SA(0, 0), cA, voffA); PG8_STAGE(PG8_SB(0, 1), cB + hstep, voffB); PG8_STAGE(PG8_SA(0, 1), cA + hstep, voffA);
;         if (wr == 1) PG8_BAR;
;         PG8_WAIT_V(4); PG8_BAR;
;         PG8_STAGE(PG8_SB(1, 0), cB + kstep, voffB); PG8_STAGE(PG8_SA(1, 0), cA + kstep, voffA); PG8_STAGE(PG8_SB(1, 1), cB + hstep + kstep, voffB);
;         PG8_WAIT_V(6); PG8_BAR;
;     }
.LBB0_431:
	v_bfe_u32 v141, v11, 4, 2
	v_and_b32_e32 v140, 15, v11
	v_lshlrev_b32_e32 v142, 4, v141
	v_lshlrev_b32_e32 v11, 2, v11
	s_and_b32 s23, s9, 3
	s_lshl_b32 s24, s8, 6
	v_lshl_or_b32 v15, v140, 6, v142
	s_lshl_b32 s8, s8, 13
	v_and_b32_e32 v11, 32, v11
	v_bitop3_b32 v16, v15, s8, v11 bitop3:0xde
	s_lshl_b32 s8, s23, 12
	v_bitop3_b32 v11, v15, s8, v11 bitop3:0xde
	s_mov_b64 s[8:9], 0x80
	s_add_i32 m0, s1, 0x18000
	v_lshl_add_u64 v[6:7], v[6:7], 0, s[8:9]
	s_waitcnt vmcnt(2)
	s_barrier
	global_load_lds_dwordx4 v[6:7], off
	v_lshl_add_u64 v[4:5], v[4:5], 0, s[8:9]
	s_add_i32 m0, s1, 0x1a000
	s_add_i32 s25, s1, 0x8000
	s_add_i32 s34, s1, 0xa000
	global_load_lds_dwordx4 v[4:5], off
	v_lshl_add_u64 v[2:3], v[2:3], 0, s[8:9]
	s_mov_b32 m0, s25
	s_add_u32 s14, s4, 0x40080
	global_load_lds_dwordx4 v[2:3], off
	v_lshl_add_u64 v[0:1], v[0:1], 0, s[8:9]
	s_mov_b32 m0, s34
	s_addc_u32 s15, s5, 0
	global_load_lds_dwordx4 v[0:1], off
	s_add_i32 m0, s1, 0x1c000
	v_lshl_add_u64 v[0:1], s[14:15], 0, v[132:133]
	global_load_lds_dwordx4 v[0:1], off
	v_lshl_add_u64 v[0:1], s[14:15], 0, v[128:129]
	s_add_i32 m0, s1, 0x1e000
	s_ashr_i32 s13, s12, 31
	global_load_lds_dwordx4 v[0:1], off
	v_lshlrev_b32_e32 v0, 14, v13
	v_and_b32_e32 v0, 0xffff8000, v0
	s_lshl_b64 s[12:13], s[12:13], 19
	v_lshl_add_u32 v0, v12, 11, v0
	v_and_b32_e32 v1, 1, v13
	s_add_u32 s12, s30, s12
	v_lshl_or_b32 v0, v1, 6, v0
	s_addc_u32 s13, s31, s13
	v_lshl_add_u32 v0, v14, 1, v0
	v_mov_b32_e32 v1, v133
	v_lshl_add_u64 v[0:1], s[12:13], 0, v[0:1]
	s_mov_b64 s[14:15], 0x7a40080
	v_lshl_add_u64 v[136:137], v[0:1], 0, s[14:15]
	v_lshlrev_b32_e32 v0, 14, v8
	v_and_b32_e32 v0, 0xffff8000, v0
	v_lshl_add_u32 v0, v9, 11, v0
	v_and_b32_e32 v1, 1, v8
	v_lshl_or_b32 v0, v1, 6, v0
	v_lshl_add_u32 v0, v10, 1, v0
	v_mov_b32_e32 v1, v133
	v_lshl_add_u64 v[0:1], s[12:13], 0, v[0:1]
	v_lshl_add_u64 v[138:139], v[0:1], 0, s[14:15]
	s_lshl_b32 s14, s74, 19
	s_add_u32 s14, s30, s14
	s_addc_u32 s15, s31, 0
	s_add_u32 s35, s14, 0x2500100
	s_waitcnt vmcnt(6)
	s_addc_u32 s38, s15, 0
	s_add_i32 s44, 0, 0x10000
	s_add_i32 s47, 0, 0x14000
	s_add_i32 s49, 0, 0x18000
	s_add_i32 s46, 0, 0x1c000
	v_add_u32_e32 v143, s44, v11
	v_add_u32_e32 v144, s47, v11
	s_add_i32 s44, s44, s61
	s_add_i32 s47, s47, s61
	v_add_u32_e32 v146, s49, v11
	s_add_i32 s49, s49, s61
	s_add_i32 s61, s46, s61
	s_mov_b32 s39, -2
	s_mov_b64 s[14:15], 0
	v_add_u32_e32 v145, 0, v16
	s_add_i32 s42, s1, 0xc000
	s_add_i32 s43, s1, 0xe000
	s_add_i32 s45, s44, 0x2000
	s_add_i32 s48, s47, 0x2000
	v_add_u32_e32 v147, s46, v11
	s_add_i32 s60, s49, 0x2000
	s_add_i32 s70, s61, 0x2000
	v_mov_b64_e32 v[0:1], 0
	v_mov_b64_e32 v[2:3], 0
	v_mov_b64_e32 v[4:5], 0
	v_mov_b64_e32 v[6:7], 0
	v_mov_b64_e32 v[16:17], 0
	v_mov_b64_e32 v[18:19], 0
	v_mov_b64_e32 v[20:21], 0
	v_mov_b64_e32 v[22:23], 0
	v_mov_b64_e32 v[32:33], 0
	v_mov_b64_e32 v[34:35], 0
	v_mov_b64_e32 v[36:37], 0
	v_mov_b64_e32 v[38:39], 0
	v_mov_b64_e32 v[48:49], 0
	v_mov_b64_e32 v[50:51], 0
	v_mov_b64_e32 v[52:53], 0
	v_mov_b64_e32 v[54:55], 0
	v_mov_b64_e32 v[8:9], 0
	v_mov_b64_e32 v[10:11], 0
	v_mov_b64_e32 v[12:13], 0
	v_mov_b64_e32 v[14:15], 0
	v_mov_b64_e32 v[24:25], 0
	v_mov_b64_e32 v[26:27], 0
	v_mov_b64_e32 v[28:29], 0
	v_mov_b64_e32 v[30:31], 0
	v_mov_b64_e32 v[40:41], 0
	v_mov_b64_e32 v[42:43], 0
	v_mov_b64_e32 v[44:45], 0
	v_mov_b64_e32 v[46:47], 0
	v_mov_b64_e32 v[56:57], 0
	v_mov_b64_e32 v[58:59], 0
	v_mov_b64_e32 v[60:61], 0
	v_mov_b64_e32 v[62:63], 0
	v_mov_b64_e32 v[64:65], 0
	v_mov_b64_e32 v[66:67], 0
	v_mov_b64_e32 v[68:69], 0
	v_mov_b64_e32 v[70:71], 0
	v_mov_b64_e32 v[80:81], 0
	v_mov_b64_e32 v[82:83], 0
	v_mov_b64_e32 v[84:85], 0
	v_mov_b64_e32 v[86:87], 0
	v_mov_b64_e32 v[96:97], 0
	v_mov_b64_e32 v[98:99], 0
	v_mov_b64_e32 v[100:101], 0
	v_mov_b64_e32 v[102:103], 0
	v_mov_b64_e32 v[112:113], 0
	v_mov_b64_e32 v[114:115], 0
	v_mov_b64_e32 v[116:117], 0
	v_mov_b64_e32 v[118:119], 0
	v_mov_b64_e32 v[72:73], 0
	v_mov_b64_e32 v[74:75], 0
	v_mov_b64_e32 v[76:77], 0
	v_mov_b64_e32 v[78:79], 0
	v_mov_b64_e32 v[88:89], 0
	v_mov_b64_e32 v[90:91], 0
	v_mov_b64_e32 v[92:93], 0
	v_mov_b64_e32 v[94:95], 0
	v_mov_b64_e32 v[104:105], 0
	v_mov_b64_e32 v[106:107], 0
	v_mov_b64_e32 v[108:109], 0
	v_mov_b64_e32 v[110:111], 0
	v_mov_b64_e32 v[120:121], 0
	v_mov_b64_e32 v[122:123], 0
	v_mov_b64_e32 v[124:125], 0
	v_mov_b64_e32 v[126:127], 0
	s_barrier

;     __device__ bool next(int i, Unit& u) const { return map((long)i * G + c, u); }
; template <class Epi, class Sched, bool ALIGN_EPI = true, bool SP2 = true>
; __device__ __forceinline__ void gemm_phase(LAS unsigned char* lds, const Gemm g, const Sched& S, const Epi& E) {
;     ...
;         const bool has_next = S.next(ui + 1, nxt);
;         const char* nA = has_next ? (const char*)g.A + (size_t)nxt.pm * tstep : cA; const char* nB = has_next ? (const char*)g.Bt + (size_t)nxt.pn * tstep : cB;
;     ...
; #pragma unroll
;         for (int a = 0; a < 2; ++a)
; #pragma unroll
;             for (int b = 0; b < 2; ++b)
; #pragma unroll
;                 for (int m = 0; m < 4; ++m)
; #pragma unroll
;                     for (int n = 0; n < 2; ++n) acc[a][b][m][n] = (f32x4){0.f, 0.f, 0.f, 0.f};
;         cur = nxt; cA = nA; cB = nB; ++ui;
.LBB0_546:
	s_ashr_i32 s89, s88, 31
	s_lshl_b64 s[10:11], s[88:89], 19
	s_add_u32 s90, s97, s10
	s_addc_u32 s91, s3, s11
	s_and_b64 s[10:11], s[4:5], exec
	s_cselect_b32 s7, s91, s15
	s_cselect_b32 s9, s90, s14
	s_ashr_i32 s79, s78, 31
	s_lshl_b64 s[10:11], s[78:79], 19
	s_add_u32 s92, s86, s10
	s_addc_u32 s93, s87, s11
	s_and_b64 s[10:11], s[4:5], exec
	s_cselect_b32 s64, s93, s13
	s_cselect_b32 s79, s92, s12
	s_add_u32 s10, s14, 0x40080
	s_addc_u32 s11, s15, 0
	s_add_u32 s85, s12, 0x100
	v_mov_b32_e32 v0, 0
	s_addc_u32 s89, s13, 0
	s_mov_b32 s94, -2
	v_mov_b32_e32 v1, v0
	v_mov_b64_e32 v[2:3], 0
	v_mov_b64_e32 v[4:5], 0
	v_mov_b64_e32 v[6:7], 0
	v_mov_b64_e32 v[16:17], 0
	v_mov_b64_e32 v[18:19], 0
	v_mov_b64_e32 v[20:21], 0
	v_mov_b64_e32 v[22:23], 0
	v_mov_b64_e32 v[32:33], 0
	v_mov_b64_e32 v[34:35], 0
	v_mov_b64_e32 v[36:37], 0
	v_mov_b64_e32 v[38:39], 0
	v_mov_b64_e32 v[48:49], 0
	v_mov_b64_e32 v[50:51], 0
	v_mov_b64_e32 v[52:53], 0
	v_mov_b64_e32 v[54:55], 0
	v_mov_b64_e32 v[8:9], 0
	v_mov_b64_e32 v[10:11], 0
	v_mov_b64_e32 v[12:13], 0
	v_mov_b64_e32 v[14:15], 0
	v_mov_b64_e32 v[24:25], 0
	v_mov_b64_e32 v[26:27], 0
	v_mov_b64_e32 v[28:29], 0
	v_mov_b64_e32 v[30:31], 0
	v_mov_b64_e32 v[40:41], 0
	v_mov_b64_e32 v[42:43], 0
	v_mov_b64_e32 v[44:45], 0
	v_mov_b64_e32 v[46:47], 0
	v_mov_b64_e32 v[56:57], 0
	v_mov_b64_e32 v[58:59], 0
	v_mov_b64_e32 v[60:61], 0
	v_mov_b64_e32 v[62:63], 0
	v_mov_b64_e32 v[64:65], 0
	v_mov_b64_e32 v[66:67], 0
	v_mov_b64_e32 v[68:69], 0
	v_mov_b64_e32 v[70:71], 0
	v_mov_b64_e32 v[80:81], 0
	v_mov_b64_e32 v[82:83], 0
	v_mov_b64_e32 v[84:85], 0
	v_mov_b64_e32 v[86:87], 0
	v_mov_b64_e32 v[96:97], 0
	v_mov_b64_e32 v[98:99], 0
	v_mov_b64_e32 v[100:101], 0
	v_mov_b64_e32 v[102:103], 0
	v_mov_b64_e32 v[112:113], 0
	v_mov_b64_e32 v[114:115], 0
	v_mov_b64_e32 v[116:117], 0
	v_mov_b64_e32 v[118:119], 0
	v_mov_b64_e32 v[72:73], 0
	v_mov_b64_e32 v[74:75], 0
	v_mov_b64_e32 v[76:77], 0
	v_mov_b64_e32 v[78:79], 0
	v_mov_b64_e32 v[88:89], 0
	v_mov_b64_e32 v[90:91], 0
	v_mov_b64_e32 v[92:93], 0
	v_mov_b64_e32 v[94:95], 0
	v_mov_b64_e32 v[104:105], 0
	v_mov_b64_e32 v[106:107], 0
	v_mov_b64_e32 v[108:109], 0
	v_mov_b64_e32 v[110:111], 0
	v_mov_b64_e32 v[120:121], 0
	v_mov_b64_e32 v[122:123], 0
	v_mov_b64_e32 v[124:125], 0
	v_mov_b64_e32 v[126:127], 0

;     __device__ bool next(int i, Unit& u) const { return map((long)i * G + c, u); }
; template <class Epi, class Sched, bool ALIGN_EPI = true, bool SP2 = true>
; __device__ __forceinline__ void gemm_phase(LAS unsigned char* lds, const Gemm g, const Sched& S, const Epi& E) {
;     ...
;         const bool has_next = S.next(ui + 1, nxt);
;         const char* nA = has_next ? (const char*)g.A + (size_t)nxt.pm * tstep : cA; const char* nB = has_next ? (const char*)g.Bt + (size_t)nxt.pn * tstep : cB;
;     ...
; #pragma unroll
;         for (int a = 0; a < 2; ++a)
; #pragma unroll
;             for (int b = 0; b < 2; ++b)
; #pragma unroll
;                 for (int m = 0; m < 4; ++m)
; #pragma unroll
;                     for (int n = 0; n < 2; ++n) acc[a][b][m][n] = (f32x4){0.f, 0.f, 0.f, 0.f};
;         cur = nxt; cA = nA; cB = nB; ++ui;
.LBB0_807:
	s_ashr_i32 s57, s56, 31
	s_lshl_b64 s[46:47], s[56:57], 19
	s_add_u32 s62, s97, s46
	s_addc_u32 s63, s3, s47
	s_and_b64 s[46:47], s[0:1], exec
	s_cselect_b32 s5, s63, s69
	s_cselect_b32 s7, s62, s68
	s_ashr_i32 s55, s54, 31
	s_lshl_b64 s[46:47], s[54:55], 19
	s_add_u32 s64, s2, s46
	s_addc_u32 s65, s16, s47
	s_and_b64 s[46:47], s[0:1], exec
	s_cselect_b32 s10, s65, s71
	s_cselect_b32 s45, s64, s70
	s_add_u32 s68, s68, 0x40080
	s_addc_u32 s69, s69, 0
	s_add_u32 s46, s70, 0x100
	v_mov_b32_e32 v0, 0
	s_addc_u32 s47, s71, 0
	s_mov_b32 s48, -2
	v_mov_b32_e32 v1, v0
	v_mov_b64_e32 v[2:3], 0
	v_mov_b64_e32 v[4:5], 0
	v_mov_b64_e32 v[6:7], 0
	v_mov_b64_e32 v[16:17], 0
	v_mov_b64_e32 v[18:19], 0
	v_mov_b64_e32 v[20:21], 0
	v_mov_b64_e32 v[22:23], 0
	v_mov_b64_e32 v[32:33], 0
	v_mov_b64_e32 v[34:35], 0
	v_mov_b64_e32 v[36:37], 0
	v_mov_b64_e32 v[38:39], 0
	v_mov_b64_e32 v[48:49], 0
	v_mov_b64_e32 v[50:51], 0
	v_mov_b64_e32 v[52:53], 0
	v_mov_b64_e32 v[54:55], 0
	v_mov_b64_e32 v[8:9], 0
	v_mov_b64_e32 v[10:11], 0
	v_mov_b64_e32 v[12:13], 0
	v_mov_b64_e32 v[14:15], 0
	v_mov_b64_e32 v[24:25], 0
	v_mov_b64_e32 v[26:27], 0
	v_mov_b64_e32 v[28:29], 0
	v_mov_b64_e32 v[30:31], 0
	v_mov_b64_e32 v[40:41], 0
	v_mov_b64_e32 v[42:43], 0
	v_mov_b64_e32 v[44:45], 0
	v_mov_b64_e32 v[46:47], 0
	v_mov_b64_e32 v[56:57], 0
	v_mov_b64_e32 v[58:59], 0
	v_mov_b64_e32 v[60:61], 0
	v_mov_b64_e32 v[62:63], 0
	v_mov_b64_e32 v[64:65], 0
	v_mov_b64_e32 v[66:67], 0
	v_mov_b64_e32 v[68:69], 0
	v_mov_b64_e32 v[70:71], 0
	v_mov_b64_e32 v[80:81], 0
	v_mov_b64_e32 v[82:83], 0
	v_mov_b64_e32 v[84:85], 0
	v_mov_b64_e32 v[86:87], 0
	v_mov_b64_e32 v[96:97], 0
	v_mov_b64_e32 v[98:99], 0
	v_mov_b64_e32 v[100:101], 0
	v_mov_b64_e32 v[102:103], 0
	v_mov_b64_e32 v[112:113], 0
	v_mov_b64_e32 v[114:115], 0
	v_mov_b64_e32 v[116:117], 0
	v_mov_b64_e32 v[118:119], 0
	v_mov_b64_e32 v[72:73], 0
	v_mov_b64_e32 v[74:75], 0
	v_mov_b64_e32 v[76:77], 0
	v_mov_b64_e32 v[78:79], 0
	v_mov_b64_e32 v[88:89], 0
	v_mov_b64_e32 v[90:91], 0
	v_mov_b64_e32 v[92:93], 0
	v_mov_b64_e32 v[94:95], 0
	v_mov_b64_e32 v[104:105], 0
	v_mov_b64_e32 v[106:107], 0
	v_mov_b64_e32 v[108:109], 0
	v_mov_b64_e32 v[110:111], 0
	v_mov_b64_e32 v[120:121], 0
	v_mov_b64_e32 v[122:123], 0
	v_mov_b64_e32 v[124:125], 0
	v_mov_b64_e32 v[126:127], 0

;     __device__ bool next(int i, Unit& u) const { return map((long)i * G + c, u); }
; template <class Epi, class Sched, bool ALIGN_EPI = true, bool SP2 = true>
; __device__ __forceinline__ void gemm_phase(LAS unsigned char* lds, const Gemm g, const Sched& S, const Epi& E) {
;     ...
;         const bool has_next = S.next(ui + 1, nxt);
;         const char* nA = has_next ? (const char*)g.A + (size_t)nxt.pm * tstep : cA; const char* nB = has_next ? (const char*)g.Bt + (size_t)nxt.pn * tstep : cB;
;     ...
; #pragma unroll
;         for (int a = 0; a < 2; ++a)
; #pragma unroll
;             for (int b = 0; b < 2; ++b)
; #pragma unroll
;                 for (int m = 0; m < 4; ++m)
; #pragma unroll
;                     for (int n = 0; n < 2; ++n) acc[a][b][m][n] = (f32x4){0.f, 0.f, 0.f, 0.f};
;         cur = nxt; cA = nA; cB = nB; ++ui;
.LBB0_1011:
	s_ashr_i32 s57, s56, 31
	s_lshl_b64 s[46:47], s[56:57], 19
	s_add_u32 s58, s21, s46
	s_addc_u32 s59, s82, s47
	s_and_b64 s[46:47], s[4:5], exec
	s_cselect_b32 s46, s59, s65
	s_cselect_b32 s47, s58, s64
	s_ashr_i32 s55, s54, 31
	s_lshl_b64 s[48:49], s[54:55], 19
	s_add_u32 s60, s88, s48
	s_addc_u32 s61, s89, s49
	s_and_b64 s[48:49], s[4:5], exec
	s_cselect_b32 s48, s61, s69
	s_cselect_b32 s49, s60, s68
	s_add_u32 s64, s64, 0x40080
	s_addc_u32 s65, s65, 0
	s_add_u32 s55, s68, 0x100
	v_mov_b32_e32 v0, 0
	s_addc_u32 s57, s69, 0
	s_mov_b32 s63, -2
	v_mov_b32_e32 v1, v0
	v_mov_b64_e32 v[2:3], 0
	v_mov_b64_e32 v[4:5], 0
	v_mov_b64_e32 v[6:7], 0
	v_mov_b64_e32 v[8:9], 0
	v_mov_b64_e32 v[10:11], 0
	v_mov_b64_e32 v[16:17], 0
	v_mov_b64_e32 v[18:19], 0
	v_mov_b64_e32 v[24:25], 0
	v_mov_b64_e32 v[26:27], 0
	v_mov_b64_e32 v[32:33], 0
	v_mov_b64_e32 v[34:35], 0
	v_mov_b64_e32 v[44:45], 0
	v_mov_b64_e32 v[46:47], 0
	v_mov_b64_e32 v[52:53], 0
	v_mov_b64_e32 v[54:55], 0
	v_mov_b64_e32 v[12:13], 0
	v_mov_b64_e32 v[14:15], 0
	v_mov_b64_e32 v[20:21], 0
	v_mov_b64_e32 v[22:23], 0
	v_mov_b64_e32 v[28:29], 0
	v_mov_b64_e32 v[30:31], 0
	v_mov_b64_e32 v[36:37], 0
	v_mov_b64_e32 v[38:39], 0
	v_mov_b64_e32 v[40:41], 0
	v_mov_b64_e32 v[42:43], 0
	v_mov_b64_e32 v[48:49], 0
	v_mov_b64_e32 v[50:51], 0
	v_mov_b64_e32 v[56:57], 0
	v_mov_b64_e32 v[58:59], 0
	v_mov_b64_e32 v[60:61], 0
	v_mov_b64_e32 v[62:63], 0
	v_mov_b64_e32 v[64:65], 0
	v_mov_b64_e32 v[66:67], 0
	v_mov_b64_e32 v[68:69], 0
	v_mov_b64_e32 v[70:71], 0
	v_mov_b64_e32 v[80:81], 0
	v_mov_b64_e32 v[82:83], 0
	v_mov_b64_e32 v[84:85], 0
	v_mov_b64_e32 v[86:87], 0
	v_mov_b64_e32 v[96:97], 0
	v_mov_b64_e32 v[98:99], 0
	v_mov_b64_e32 v[100:101], 0
	v_mov_b64_e32 v[102:103], 0
	v_mov_b64_e32 v[108:109], 0
	v_mov_b64_e32 v[110:111], 0
	v_mov_b64_e32 v[116:117], 0
	v_mov_b64_e32 v[118:119], 0
	v_mov_b64_e32 v[72:73], 0
	v_mov_b64_e32 v[74:75], 0
	v_mov_b64_e32 v[76:77], 0
	v_mov_b64_e32 v[78:79], 0
	v_mov_b64_e32 v[88:89], 0
	v_mov_b64_e32 v[90:91], 0
	v_mov_b64_e32 v[92:93], 0
	v_mov_b64_e32 v[94:95], 0
	v_mov_b64_e32 v[104:105], 0
	v_mov_b64_e32 v[106:107], 0
	v_mov_b64_e32 v[112:113], 0
	v_mov_b64_e32 v[114:115], 0
	v_mov_b64_e32 v[120:121], 0
	v_mov_b64_e32 v[122:123], 0
	v_mov_b64_e32 v[124:125], 0
	v_mov_b64_e32 v[126:127], 0

;     __device__ bool next(int i, Unit& u) const { return map((long)i * G + c, u); }
; template <class Epi, class Sched, bool ALIGN_EPI = true, bool SP2 = true>
; __device__ __forceinline__ void gemm_phase(LAS unsigned char* lds, const Gemm g, const Sched& S, const Epi& E) {
;     ...
;         const bool has_next = S.next(ui + 1, nxt);
;         const char* nA = has_next ? (const char*)g.A + (size_t)nxt.pm * tstep : cA; const char* nB = has_next ? (const char*)g.Bt + (size_t)nxt.pn * tstep : cB;
;     ...
; #pragma unroll
;         for (int a = 0; a < 2; ++a)
; #pragma unroll
;             for (int b = 0; b < 2; ++b)
; #pragma unroll
;                 for (int m = 0; m < 4; ++m)
; #pragma unroll
;                     for (int n = 0; n < 2; ++n) acc[a][b][m][n] = (f32x4){0.f, 0.f, 0.f, 0.f};
;         cur = nxt; cA = nA; cB = nB; ++ui;
.LBB0_1036:
	s_ashr_i32 s61, s60, 31
	s_lshl_b64 s[44:45], s[60:61], 19
	s_add_u32 s62, s26, s44
	s_addc_u32 s63, s27, s45
	s_and_b64 s[44:45], s[4:5], exec
	s_cselect_b32 s43, s63, s71
	s_cselect_b32 s44, s62, s70
	s_ashr_i32 s59, s58, 31
	s_lshl_b64 s[46:47], s[58:59], 19
	s_add_u32 s64, s82, s46
	s_addc_u32 s65, s83, s47
	s_and_b64 s[46:47], s[4:5], exec
	s_cselect_b32 s45, s65, s73
	s_cselect_b32 s46, s64, s72
	s_add_u32 s70, s70, 0x40080
	s_addc_u32 s71, s71, 0
	s_add_u32 s47, s72, 0x100
	v_mov_b32_e32 v0, 0
	s_addc_u32 s48, s73, 0
	s_mov_b32 s49, -2
	v_mov_b32_e32 v1, v0
	v_mov_b64_e32 v[2:3], 0
	v_mov_b64_e32 v[4:5], 0
	v_mov_b64_e32 v[6:7], 0
	v_mov_b64_e32 v[16:17], 0
	v_mov_b64_e32 v[18:19], 0
	v_mov_b64_e32 v[20:21], 0
	v_mov_b64_e32 v[22:23], 0
	v_mov_b64_e32 v[32:33], 0
	v_mov_b64_e32 v[34:35], 0
	v_mov_b64_e32 v[36:37], 0
	v_mov_b64_e32 v[38:39], 0
	v_mov_b64_e32 v[48:49], 0
	v_mov_b64_e32 v[50:51], 0
	v_mov_b64_e32 v[52:53], 0
	v_mov_b64_e32 v[54:55], 0
	v_mov_b64_e32 v[8:9], 0
	v_mov_b64_e32 v[10:11], 0
	v_mov_b64_e32 v[12:13], 0
	v_mov_b64_e32 v[14:15], 0
	v_mov_b64_e32 v[24:25], 0
	v_mov_b64_e32 v[26:27], 0
	v_mov_b64_e32 v[28:29], 0
	v_mov_b64_e32 v[30:31], 0
	v_mov_b64_e32 v[40:41], 0
	v_mov_b64_e32 v[42:43], 0
	v_mov_b64_e32 v[44:45], 0
	v_mov_b64_e32 v[46:47], 0
	v_mov_b64_e32 v[56:57], 0
	v_mov_b64_e32 v[58:59], 0
	v_mov_b64_e32 v[60:61], 0
	v_mov_b64_e32 v[62:63], 0
	v_mov_b64_e32 v[64:65], 0
	v_mov_b64_e32 v[66:67], 0
	v_mov_b64_e32 v[68:69], 0
	v_mov_b64_e32 v[70:71], 0
	v_mov_b64_e32 v[80:81], 0
	v_mov_b64_e32 v[82:83], 0
	v_mov_b64_e32 v[84:85], 0
	v_mov_b64_e32 v[86:87], 0
	v_mov_b64_e32 v[96:97], 0
	v_mov_b64_e32 v[98:99], 0
	v_mov_b64_e32 v[100:101], 0
	v_mov_b64_e32 v[102:103], 0
	v_mov_b64_e32 v[112:113], 0
	v_mov_b64_e32 v[114:115], 0
	v_mov_b64_e32 v[116:117], 0
	v_mov_b64_e32 v[118:119], 0
	v_mov_b64_e32 v[72:73], 0
	v_mov_b64_e32 v[74:75], 0
	v_mov_b64_e32 v[76:77], 0
	v_mov_b64_e32 v[78:79], 0
	v_mov_b64_e32 v[88:89], 0
	v_mov_b64_e32 v[90:91], 0
	v_mov_b64_e32 v[92:93], 0
	v_mov_b64_e32 v[94:95], 0
	v_mov_b64_e32 v[104:105], 0
	v_mov_b64_e32 v[106:107], 0
	v_mov_b64_e32 v[108:109], 0
	v_mov_b64_e32 v[110:111], 0
	v_mov_b64_e32 v[120:121], 0
	v_mov_b64_e32 v[122:123], 0
	v_mov_b64_e32 v[124:125], 0
	v_mov_b64_e32 v[126:127], 0

;     __device__ bool next(int i, Unit& u) const { return map((long)i * G + c, u); }
; template <class Epi, class Sched, bool ALIGN_EPI = true, bool SP2 = true>
; __device__ __forceinline__ void gemm_phase(LAS unsigned char* lds, const Gemm g, const Sched& S, const Epi& E) {
;     ...
;         const bool has_next = S.next(ui + 1, nxt);
;         const char* nA = has_next ? (const char*)g.A + (size_t)nxt.pm * tstep : cA; const char* nB = has_next ? (const char*)g.Bt + (size_t)nxt.pn * tstep : cB;
;     ...
; #pragma unroll
;         for (int a = 0; a < 2; ++a)
; #pragma unroll
;             for (int b = 0; b < 2; ++b)
; #pragma unroll
;                 for (int m = 0; m < 4; ++m)
; #pragma unroll
;                     for (int n = 0; n < 2; ++n) acc[a][b][m][n] = (f32x4){0.f, 0.f, 0.f, 0.f};
;         cur = nxt; cA = nA; cB = nB; ++ui;
.LBB0_1112:
	s_ashr_i32 s59, s58, 31
	s_lshl_b64 s[60:61], s[58:59], 19
	s_add_u32 s60, s28, s60
	s_addc_u32 s61, s29, s61
	s_and_b64 s[62:63], s[4:5], exec
	s_cselect_b32 s49, s61, s65
	s_cselect_b32 s55, s60, s64
	s_ashr_i32 s57, s56, 31
	s_lshl_b64 s[62:63], s[56:57], 19
	s_add_u32 s62, s80, s62
	s_addc_u32 s63, s81, s63
	s_and_b64 s[70:71], s[4:5], exec
	s_cselect_b32 s57, s63, s69
	s_cselect_b32 s59, s62, s68
	s_add_u32 s64, s64, 0x40080
	s_addc_u32 s65, s65, 0
	s_add_u32 s72, s68, 0x100
	v_mov_b32_e32 v0, 0
	s_addc_u32 s73, s69, 0
	s_mov_b32 s74, -2
	v_mov_b32_e32 v1, v0
	v_mov_b64_e32 v[2:3], 0
	v_mov_b64_e32 v[4:5], 0
	v_mov_b64_e32 v[6:7], 0
	v_mov_b64_e32 v[8:9], 0
	v_mov_b64_e32 v[10:11], 0
	v_mov_b64_e32 v[12:13], 0
	v_mov_b64_e32 v[14:15], 0
	v_mov_b64_e32 v[24:25], 0
	v_mov_b64_e32 v[26:27], 0
	v_mov_b64_e32 v[28:29], 0
	v_mov_b64_e32 v[30:31], 0
	v_mov_b64_e32 v[40:41], 0
	v_mov_b64_e32 v[42:43], 0
	v_mov_b64_e32 v[44:45], 0
	v_mov_b64_e32 v[46:47], 0
	v_mov_b64_e32 v[16:17], 0
	v_mov_b64_e32 v[18:19], 0
	v_mov_b64_e32 v[20:21], 0
	v_mov_b64_e32 v[22:23], 0
	v_mov_b64_e32 v[32:33], 0
	v_mov_b64_e32 v[34:35], 0
	v_mov_b64_e32 v[36:37], 0
	v_mov_b64_e32 v[38:39], 0
	v_mov_b64_e32 v[48:49], 0
	v_mov_b64_e32 v[50:51], 0
	v_mov_b64_e32 v[52:53], 0
	v_mov_b64_e32 v[54:55], 0
	v_mov_b64_e32 v[56:57], 0
	v_mov_b64_e32 v[58:59], 0
	v_mov_b64_e32 v[60:61], 0
	v_mov_b64_e32 v[62:63], 0
	v_mov_b64_e32 v[64:65], 0
	v_mov_b64_e32 v[66:67], 0
	v_mov_b64_e32 v[68:69], 0
	v_mov_b64_e32 v[70:71], 0
	v_mov_b64_e32 v[72:73], 0
	v_mov_b64_e32 v[74:75], 0
	v_mov_b64_e32 v[76:77], 0
	v_mov_b64_e32 v[78:79], 0
	v_mov_b64_e32 v[88:89], 0
	v_mov_b64_e32 v[90:91], 0
	v_mov_b64_e32 v[92:93], 0
	v_mov_b64_e32 v[94:95], 0
	v_mov_b64_e32 v[104:105], 0
	v_mov_b64_e32 v[106:107], 0
	v_mov_b64_e32 v[108:109], 0
	v_mov_b64_e32 v[110:111], 0
	v_mov_b64_e32 v[80:81], 0
	v_mov_b64_e32 v[82:83], 0
	v_mov_b64_e32 v[84:85], 0
	v_mov_b64_e32 v[86:87], 0
	v_mov_b64_e32 v[96:97], 0
	v_mov_b64_e32 v[98:99], 0
	v_mov_b64_e32 v[100:101], 0
	v_mov_b64_e32 v[102:103], 0
	v_mov_b64_e32 v[112:113], 0
	v_mov_b64_e32 v[114:115], 0
	v_mov_b64_e32 v[116:117], 0
	v_mov_b64_e32 v[118:119], 0
	v_mov_b64_e32 v[120:121], 0
	v_mov_b64_e32 v[122:123], 0
	v_mov_b64_e32 v[124:125], 0
	v_mov_b64_e32 v[126:127], 0

;     __device__ bool next(int i, Unit& u) const { return map((long)i * G + c, u); }
; template <class Epi, class Sched, bool ALIGN_EPI = true, bool SP2 = true>
; __device__ __forceinline__ void gemm_phase(LAS unsigned char* lds, const Gemm g, const Sched& S, const Epi& E) {
;     ...
;         const bool has_next = S.next(ui + 1, nxt);
;         const char* nA = has_next ? (const char*)g.A + (size_t)nxt.pm * tstep : cA; const char* nB = has_next ? (const char*)g.Bt + (size_t)nxt.pn * tstep : cB;
;     ...
; #pragma unroll
;         for (int a = 0; a < 2; ++a)
; #pragma unroll
;             for (int b = 0; b < 2; ++b)
; #pragma unroll
;                 for (int m = 0; m < 4; ++m)
; #pragma unroll
;                     for (int n = 0; n < 2; ++n) acc[a][b][m][n] = (f32x4){0.f, 0.f, 0.f, 0.f};
;         cur = nxt; cA = nA; cB = nB; ++ui;
.LBB0_1235:
	s_ashr_i32 s37, s36, 31
	s_lshl_b64 s[40:41], s[36:37], 19
	s_add_u32 s40, s97, s40
	s_addc_u32 s41, s3, s41
	s_and_b64 s[42:43], s[6:7], exec
	s_cselect_b32 s37, s41, s47
	s_cselect_b32 s54, s40, s46
	s_ashr_i32 s15, s14, 31
	s_lshl_b64 s[42:43], s[14:15], 19
	s_add_u32 s42, s62, s42
	s_addc_u32 s43, s63, s43
	s_and_b64 s[50:51], s[6:7], exec
	s_cselect_b32 s15, s43, s49
	s_cselect_b32 s55, s42, s48
	s_add_u32 s46, s46, 0x40080
	s_addc_u32 s47, s47, 0
	s_add_u32 s56, s48, 0x100
	v_mov_b32_e32 v0, 0
	s_addc_u32 s57, s49, 0
	s_mov_b32 s58, -2
	v_mov_b32_e32 v1, v0
	v_mov_b64_e32 v[2:3], 0
	v_mov_b64_e32 v[4:5], 0
	v_mov_b64_e32 v[6:7], 0
	v_mov_b64_e32 v[16:17], 0
	v_mov_b64_e32 v[18:19], 0
	v_mov_b64_e32 v[20:21], 0
	v_mov_b64_e32 v[22:23], 0
	v_mov_b64_e32 v[32:33], 0
	v_mov_b64_e32 v[34:35], 0
	v_mov_b64_e32 v[36:37], 0
	v_mov_b64_e32 v[38:39], 0
	v_mov_b64_e32 v[48:49], 0
	v_mov_b64_e32 v[50:51], 0
	v_mov_b64_e32 v[52:53], 0
	v_mov_b64_e32 v[54:55], 0
	v_mov_b64_e32 v[8:9], 0
	v_mov_b64_e32 v[10:11], 0
	v_mov_b64_e32 v[12:13], 0
	v_mov_b64_e32 v[14:15], 0
	v_mov_b64_e32 v[24:25], 0
	v_mov_b64_e32 v[26:27], 0
	v_mov_b64_e32 v[28:29], 0
	v_mov_b64_e32 v[30:31], 0
	v_mov_b64_e32 v[40:41], 0
	v_mov_b64_e32 v[42:43], 0
	v_mov_b64_e32 v[44:45], 0
	v_mov_b64_e32 v[46:47], 0
	v_mov_b64_e32 v[56:57], 0
	v_mov_b64_e32 v[58:59], 0
	v_mov_b64_e32 v[60:61], 0
	v_mov_b64_e32 v[62:63], 0
	v_mov_b64_e32 v[64:65], 0
	v_mov_b64_e32 v[66:67], 0
	v_mov_b64_e32 v[68:69], 0
	v_mov_b64_e32 v[70:71], 0
	v_mov_b64_e32 v[80:81], 0
	v_mov_b64_e32 v[82:83], 0
	v_mov_b64_e32 v[84:85], 0
	v_mov_b64_e32 v[86:87], 0
	v_mov_b64_e32 v[96:97], 0
	v_mov_b64_e32 v[98:99], 0
	v_mov_b64_e32 v[100:101], 0
	v_mov_b64_e32 v[102:103], 0
	v_mov_b64_e32 v[112:113], 0
	v_mov_b64_e32 v[114:115], 0
	v_mov_b64_e32 v[116:117], 0
	v_mov_b64_e32 v[118:119], 0
	v_mov_b64_e32 v[72:73], 0
	v_mov_b64_e32 v[74:75], 0
	v_mov_b64_e32 v[76:77], 0
	v_mov_b64_e32 v[78:79], 0
	v_mov_b64_e32 v[88:89], 0
	v_mov_b64_e32 v[90:91], 0
	v_mov_b64_e32 v[92:93], 0
	v_mov_b64_e32 v[94:95], 0
	v_mov_b64_e32 v[104:105], 0
	v_mov_b64_e32 v[106:107], 0
	v_mov_b64_e32 v[108:109], 0
	v_mov_b64_e32 v[110:111], 0
	v_mov_b64_e32 v[120:121], 0
	v_mov_b64_e32 v[122:123], 0
	v_mov_b64_e32 v[124:125], 0
	v_mov_b64_e32 v[126:127], 0

; template <class Epi, class Sched, bool ALIGN_EPI = true, bool SP2 = true>
; __device__ __forceinline__ void gemm_phase(LAS unsigned char* lds, const Gemm g, const Sched& S, const Epi& E) {
;     ...
; #pragma unroll
;         for (int a = 0; a < 2; ++a)
; #pragma unroll
;             for (int b = 0; b < 2; ++b)
; #pragma unroll
;                 for (int m = 0; m < 4; ++m)
; #pragma unroll
;                     for (int n = 0; n < 2; ++n) acc[a][b][m][n] = (f32x4){0.f, 0.f, 0.f, 0.f};
;         cur = nxt; cA = nA; cB = nB; ++ui;
.LBB0_1315:
	s_add_u32 s63, s48, 0x100
	v_mov_b32_e32 v0, 0
	s_addc_u32 s64, s49, 0
	s_mov_b32 s65, -2
	v_mov_b32_e32 v1, v0
	v_mov_b64_e32 v[2:3], 0
	v_mov_b64_e32 v[4:5], 0
	v_mov_b64_e32 v[6:7], 0
	v_mov_b64_e32 v[8:9], 0
	v_mov_b64_e32 v[10:11], 0
	v_mov_b64_e32 v[12:13], 0
	v_mov_b64_e32 v[14:15], 0
	v_mov_b64_e32 v[24:25], 0
	v_mov_b64_e32 v[26:27], 0
	v_mov_b64_e32 v[28:29], 0
	v_mov_b64_e32 v[30:31], 0
	v_mov_b64_e32 v[40:41], 0
	v_mov_b64_e32 v[42:43], 0
	v_mov_b64_e32 v[44:45], 0
	v_mov_b64_e32 v[46:47], 0
	v_mov_b64_e32 v[16:17], 0
	v_mov_b64_e32 v[18:19], 0
	v_mov_b64_e32 v[20:21], 0
	v_mov_b64_e32 v[22:23], 0
	v_mov_b64_e32 v[32:33], 0
	v_mov_b64_e32 v[34:35], 0
	v_mov_b64_e32 v[36:37], 0
	v_mov_b64_e32 v[38:39], 0
	v_mov_b64_e32 v[48:49], 0
	v_mov_b64_e32 v[50:51], 0
	v_mov_b64_e32 v[52:53], 0
	v_mov_b64_e32 v[54:55], 0
	v_mov_b64_e32 v[56:57], 0
	v_mov_b64_e32 v[58:59], 0
	v_mov_b64_e32 v[60:61], 0
	v_mov_b64_e32 v[62:63], 0
	v_mov_b64_e32 v[64:65], 0
	v_mov_b64_e32 v[66:67], 0
	v_mov_b64_e32 v[68:69], 0
	v_mov_b64_e32 v[70:71], 0
	v_mov_b64_e32 v[72:73], 0
	v_mov_b64_e32 v[74:75], 0
	v_mov_b64_e32 v[76:77], 0
	v_mov_b64_e32 v[78:79], 0
	v_mov_b64_e32 v[88:89], 0
	v_mov_b64_e32 v[90:91], 0
	v_mov_b64_e32 v[92:93], 0
	v_mov_b64_e32 v[94:95], 0
	v_mov_b64_e32 v[104:105], 0
	v_mov_b64_e32 v[106:107], 0
	v_mov_b64_e32 v[108:109], 0
	v_mov_b64_e32 v[110:111], 0
	v_mov_b64_e32 v[80:81], 0
	v_mov_b64_e32 v[82:83], 0
	v_mov_b64_e32 v[84:85], 0
	v_mov_b64_e32 v[86:87], 0
	v_mov_b64_e32 v[96:97], 0
	v_mov_b64_e32 v[98:99], 0
	v_mov_b64_e32 v[100:101], 0
	v_mov_b64_e32 v[102:103], 0
	v_mov_b64_e32 v[112:113], 0
	v_mov_b64_e32 v[114:115], 0
	v_mov_b64_e32 v[116:117], 0
	v_mov_b64_e32 v[118:119], 0
	v_mov_b64_e32 v[120:121], 0
	v_mov_b64_e32 v[122:123], 0
	v_mov_b64_e32 v[124:125], 0
	v_mov_b64_e32 v[126:127], 0
